# v29 with the V-fragment prologue reads moved from the VALU segment into the head of the wave's own P.V MFMA segment (no LDS reads in the partner's MFMA window)
# baseline (speedup 1.0000x reference)
; #define SBAR() __builtin_amdgcn_sched_barrier(0)
; #define QKT(P0, P1, KS) do { if (MODE == 1) qkt_lds(P0, P1, KS, qs, r32, hi); else qkt(P0, P1, KS, qr, r32, hi); } while (0)
; __device__ __forceinline__ void finishSM(f32x16& p0, f32x16& p1, float alpha, float& l_reg, bf16x8& pa0, bf16x8& pa1, bf16x8& pa2, bf16x8& pa3) {
;   for (int r = 0; r < 16; ++r) p1[r] = __builtin_amdgcn_exp2f(p1[r]);
;   float ps = 0; for (int r = 0; r < 16; ++r) ps += p0[r]; for (int r = 0; r < 16; ++r) ps += p1[r];
;   { auto rr = __builtin_amdgcn_permlane32_swap(__float_as_uint(ps), __float_as_uint(ps), false, false);
;     ps = __uint_as_float(rr[0]) + __uint_as_float(rr[1]); }
;   l_reg = l_reg * alpha + ps;
;     ...
;   PK4(p0, 0, pa0); PK4(p0, 8, pa1); PK4(p1, 0, pa2); PK4(p1, 8, pa3);
;     ...
; }
; __device__ __forceinline__ void qkt(f32x16& p0, f32x16& p1, const u16* Ks, const bf16x8* qr, int r32, int hi) {
;   p0 = f32x16{}; p1 = f32x16{};
;   for (int d0 = 0; d0 < 8; ++d0) { int cb = (d0 * 16 + hi * 8) * 2;
;     bf16x8 b0 = *reinterpret_cast<const bf16x8*>((const char*)Ks + KSWZ(r32, cb));
;     bf16x8 b1 = *reinterpret_cast<const bf16x8*>((const char*)Ks + KSWZ(32 + r32, cb));
;     p0 = __builtin_amdgcn_mfma_f32_32x32x16_bf16(b0, qr[d0], p0, 0, 0, 0);
;     p1 = __builtin_amdgcn_mfma_f32_32x32x16_bf16(b1, qr[d0], p1, 0, 0, 0); }
; }
; template <int MODE> ...
;     ...
;     for (int j = 1; j + 1 < NT; j += 2) {
;       const int s0_ = sj, s1_ = sj == 2 ? 0 : sj + 1, s2_ = s1_ == 2 ? 0 : s1_ + 1;
;       SBAR(); QKT(pB0, pB1, (u16*)((char*)K_lds + s0_ * SHM_K));
;       finishSM(pA0, pA1, alA, l_reg, pa0, pa1, pa2, pa3); SBAR();
;       { const int tn = (j + 2 < NT) ? j + 2 : NT - 1; SLOAD(SO, tn); } SBAR();
.LBB0_474:
	s_add_i32 s7, s89, 1
	s_cmp_lg_u32 s89, 2
	s_cselect_b32 s66, s7, 0
	s_add_i32 s7, s66, 1
	s_cmp_lg_u32 s66, 2
	s_mov_b32 s6, s89
	s_cselect_b32 s89, s7, 0
	s_lshl_b32 s93, s6, 14
	s_add_i32 s6, s93, 0
	s_setprio 1
	v_add_u32_e32 v254, s6, v189
	ds_read_b128 v[68:71], v254 offset:49152
	ds_read_b128 v[72:75], v254 offset:49280
	v_add_u32_e32 v254, s6, v190
	ds_read_b128 v[76:79], v254 offset:49152
	ds_read_b128 v[80:83], v254 offset:49280
	v_add_u32_e32 v254, s6, v191
	ds_read_b128 v[220:223], v254 offset:49152
	ds_read_b128 v[224:227], v254 offset:49280
	v_add_u32_e32 v254, s6, v192
	ds_read_b128 v[228:231], v254 offset:49152
	ds_read_b128 v[232:235], v254 offset:49280
	v_add_u32_e32 v254, s6, v189
	ds_read_b128 v[236:239], v254 offset:57344
	ds_read_b128 v[240:243], v254 offset:57472
	s_waitcnt lgkmcnt(9)
	v_mfma_f32_32x32x16_bf16 v[84:99], v[68:71], v[100:103], 0
	s_waitcnt lgkmcnt(8)
	v_mfma_f32_32x32x16_bf16 v[84:99], v[72:75], v[116:119], v[84:99]
	s_waitcnt lgkmcnt(7)
	v_mfma_f32_32x32x16_bf16 v[84:99], v[76:79], v[104:107], v[84:99]
	s_waitcnt lgkmcnt(6)
	v_mfma_f32_32x32x16_bf16 v[84:99], v[80:83], v[120:123], v[84:99]
	s_waitcnt lgkmcnt(5)
	v_mfma_f32_32x32x16_bf16 v[84:99], v[220:223], v[108:111], v[84:99]
	v_add_u32_e32 v254, s6, v190
	ds_read_b128 v[220:223], v254 offset:57344
	s_waitcnt lgkmcnt(5)
	v_mfma_f32_32x32x16_bf16 v[84:99], v[224:227], v[124:127], v[84:99]
	ds_read_b128 v[224:227], v254 offset:57472
	s_waitcnt lgkmcnt(5)
	v_mfma_f32_32x32x16_bf16 v[84:99], v[228:231], v[112:115], v[84:99]
	v_add_u32_e32 v254, s6, v191
	ds_read_b128 v[228:231], v254 offset:57344
	s_waitcnt lgkmcnt(5)
	v_mfma_f32_32x32x16_bf16 v[84:99], v[232:235], v[128:131], v[84:99]
	ds_read_b128 v[232:235], v254 offset:57472
	s_waitcnt lgkmcnt(5)
	v_mfma_f32_32x32x16_bf16 v[68:83], v[236:239], v[100:103], 0
	v_add_u32_e32 v254, s6, v192
	ds_read_b128 v[236:239], v254 offset:57344
	s_waitcnt lgkmcnt(5)
	v_mfma_f32_32x32x16_bf16 v[68:83], v[240:243], v[116:119], v[68:83]
	ds_read_b128 v[240:243], v254 offset:57472
	s_waitcnt lgkmcnt(5)
	v_mfma_f32_32x32x16_bf16 v[68:83], v[220:223], v[104:107], v[68:83]
	s_waitcnt lgkmcnt(4)
	v_mfma_f32_32x32x16_bf16 v[68:83], v[224:227], v[120:123], v[68:83]
	s_waitcnt lgkmcnt(3)
	v_mfma_f32_32x32x16_bf16 v[68:83], v[228:231], v[108:111], v[68:83]
	s_waitcnt lgkmcnt(2)
	v_mfma_f32_32x32x16_bf16 v[68:83], v[232:235], v[124:127], v[68:83]
	s_waitcnt lgkmcnt(1)
	v_mfma_f32_32x32x16_bf16 v[68:83], v[236:239], v[112:115], v[68:83]
	s_waitcnt lgkmcnt(0)
	v_mfma_f32_32x32x16_bf16 v[68:83], v[240:243], v[128:131], v[68:83]
	s_setprio 0
	s_barrier
	v_exp_f32_e32 v160, v160
	v_exp_f32_e32 v161, v161
	v_exp_f32_e32 v158, v158
	v_exp_f32_e32 v159, v159
	v_exp_f32_e32 v156, v156
	v_exp_f32_e32 v157, v157
	v_exp_f32_e32 v154, v154
	v_exp_f32_e32 v155, v155
	v_exp_f32_e32 v152, v152
	v_exp_f32_e32 v153, v153
	v_exp_f32_e32 v150, v150
	v_exp_f32_e32 v151, v151
	v_exp_f32_e32 v148, v148
	v_exp_f32_e32 v149, v149
	v_exp_f32_e32 v2, v162
	v_exp_f32_e32 v162, v163
	v_add_f32_e32 v163, 0, v216
	v_add_f32_e32 v163, v218, v163
	v_add_f32_e32 v163, v214, v163
	v_add_f32_e32 v163, v217, v163
	v_add_f32_e32 v163, v213, v163
	v_add_f32_e32 v163, v215, v163
	v_add_f32_e32 v163, v211, v163
	v_add_f32_e32 v163, v212, v163
	v_add_f32_e32 v163, v208, v163
	v_add_f32_e32 v163, v210, v163
	v_add_f32_e32 v163, v207, v163
	v_add_f32_e32 v163, v209, v163
	v_add_f32_e32 v163, v204, v163
	v_add_f32_e32 v163, v206, v163
	v_add_f32_e32 v163, v203, v163
	v_add_f32_e32 v163, v205, v163
	v_add_f32_e32 v163, v2, v163
	v_add_f32_e32 v163, v162, v163
	v_add_f32_e32 v163, v160, v163
	v_add_f32_e32 v163, v161, v163
	v_add_f32_e32 v163, v158, v163
	v_add_f32_e32 v163, v159, v163
	v_add_f32_e32 v163, v156, v163
	v_add_f32_e32 v163, v157, v163
	v_add_f32_e32 v163, v154, v163
	v_add_f32_e32 v163, v155, v163
	v_add_f32_e32 v163, v152, v163
	v_add_f32_e32 v163, v153, v163
	v_add_f32_e32 v163, v150, v163
	v_add_f32_e32 v163, v151, v163
	v_add_f32_e32 v163, v148, v163
	v_add_f32_e32 v200, v149, v163
	v_mov_b32_e32 v201, v200
	v_cvt_pk_bf16_f32 v216, v216, v218
	v_cvt_pk_bf16_f32 v217, v214, v217
	v_cvt_pk_bf16_f32 v218, v213, v215
	v_cvt_pk_bf16_f32 v219, v211, v212
	v_cvt_pk_bf16_f32 v208, v208, v210
	v_cvt_pk_bf16_f32 v209, v207, v209
	v_cvt_pk_bf16_f32 v210, v204, v206
	v_cvt_pk_bf16_f32 v211, v203, v205
	v_cvt_pk_bf16_f32 v202, v2, v162
	v_cvt_pk_bf16_f32 v203, v160, v161
	v_cvt_pk_bf16_f32 v204, v158, v159
	v_permlane32_swap_b32_e32 v200, v201
	v_cvt_pk_bf16_f32 v205, v156, v157
	v_permlane32_swap_b32_e32 v202, v204
	v_cvt_pk_bf16_f32 v212, v154, v155
	v_cvt_pk_bf16_f32 v213, v152, v153
	v_cvt_pk_bf16_f32 v214, v150, v151
	v_cvt_pk_bf16_f32 v215, v148, v149
	v_permlane32_swap_b32_e32 v216, v218
	v_permlane32_swap_b32_e32 v217, v219
	v_permlane32_swap_b32_e32 v208, v210
	v_permlane32_swap_b32_e32 v209, v211
	v_permlane32_swap_b32_e32 v203, v205
	v_permlane32_swap_b32_e32 v212, v214
	v_permlane32_swap_b32_e32 v213, v215
	s_add_i32 s91, s16, -1
	s_min_u32 s7, s91, s90
	s_add_i32 s7, s7, s88
	s_lshl_b32 s7, s7, 6
	v_add_u32_e32 v244, s7, v167
	v_add_u32_e32 v245, s7, v185
	v_lshl_or_b32 v244, v244, 8, v182
	v_lshl_or_b32 v245, v245, 8, v182
	global_load_dwordx4 v[152:155], v244, s[58:59]
	global_load_dwordx4 v[148:151], v245, s[58:59]
	global_load_dwordx4 v[160:163], v244, s[64:65]
	global_load_dwordx4 v[156:159], v245, s[64:65]
	s_lshl_b32 s94, s89, 14
	s_barrier
; #define SBAR() __builtin_amdgcn_sched_barrier(0)
; __device__ __forceinline__ void partialSM(f32x16& p0, f32x16& p1, float& m_reg, float& mn, float& alpha) {
;   constexpr float C = SCALE * 1.4426950408889634f;
;   float pmax = p0[0]; for (int r = 1; r < 16; ++r) pmax = fmaxf(pmax, p0[r]); for (int r = 0; r < 16; ++r) pmax = fmaxf(pmax, p1[r]);
;   { auto rr = __builtin_amdgcn_permlane32_swap(__float_as_uint(pmax), __float_as_uint(pmax), false, false);
;     pmax = fmaxf(__uint_as_float(rr[0]), __uint_as_float(rr[1])); }
;   if (__builtin_expect(__all(pmax - m_reg <= THR / SCALE), 1)) { mn = m_reg; alpha = 1.f; }
;   else { mn = fmaxf(m_reg, pmax); alpha = __builtin_amdgcn_exp2f((m_reg - mn) * C); m_reg = mn; }
; template <int OFF> __device__ __forceinline__ s16x4 tr_read(int vb) {
;   s16x4 r; asm volatile("ds_read_b64_tr_b16 %0, %1 offset:%2" : "=&v"(r) : "v"(vb), "i"(OFF) : "memory"); return r;
; }
; template <int D0> __device__ __forceinline__ void pv_one(f32x16& od, int vb, bf16x8 pa0, bf16x8 pa1, bf16x8 pa2, bf16x8 pa3) {
;   const s16x4 l0 = tr_read<v_rd_off(D0, 0, 0)>(vb), h0 = tr_read<v_rd_off(D0, 0, 1)>(vb), l1 = tr_read<v_rd_off(D0, 1, 0)>(vb), h1 = tr_read<v_rd_off(D0, 1, 1)>(vb);
;   const s16x4 l2 = tr_read<v_rd_off(D0, 2, 0)>(vb), h2 = tr_read<v_rd_off(D0, 2, 1)>(vb), l3 = tr_read<v_rd_off(D0, 3, 0)>(vb), h3 = tr_read<v_rd_off(D0, 3, 1)>(vb);
;   asm volatile("s_waitcnt lgkmcnt(0)" ::: "memory"); SBAR();
;     ...
;   od = __builtin_amdgcn_mfma_f32_32x32x16_bf16(pa0, PK(l0, h0), od, 0, 0, 0);
;   od = __builtin_amdgcn_mfma_f32_32x32x16_bf16(pa1, PK(l1, h1), od, 0, 0, 0);
;   od = __builtin_amdgcn_mfma_f32_32x32x16_bf16(pa2, PK(l2, h2), od, 0, 0, 0);
;   od = __builtin_amdgcn_mfma_f32_32x32x16_bf16(pa3, PK(l3, h3), od, 0, 0, 0);
;     ...
; }
; __device__ __forceinline__ void pv_d0(f32x16* o, int vb, bf16x8 pa0, bf16x8 pa1, bf16x8 pa2, bf16x8 pa3) {
;   pv_one<0>(o[0], vb, pa0, pa1, pa2, pa3); pv_one<1>(o[1], vb, pa0, pa1, pa2, pa3); pv_one<2>(o[2], vb, pa0, pa1, pa2, pa3); pv_one<3>(o[3], vb, pa0, pa1, pa2, pa3);
	s_setprio 1
	v_add_u32_e32 v254, s94, v197
	ds_read_b64_tr_b16 v[220:221], v254 offset:0
	ds_read_b64_tr_b16 v[222:223], v254 offset:2048
	ds_read_b64_tr_b16 v[224:225], v254 offset:4096
	ds_read_b64_tr_b16 v[226:227], v254 offset:6144
	ds_read_b64_tr_b16 v[228:229], v254 offset:8192
	ds_read_b64_tr_b16 v[230:231], v254 offset:10240
	ds_read_b64_tr_b16 v[232:233], v254 offset:12288
	ds_read_b64_tr_b16 v[234:235], v254 offset:14336
	ds_read_b64_tr_b16 v[236:237], v254 offset:512
	ds_read_b64_tr_b16 v[238:239], v254 offset:2560
	s_waitcnt lgkmcnt(6)
	v_mfma_f32_32x32x16_bf16 v[52:67], v[216:219], v[220:223], v[52:67]
	ds_read_b64_tr_b16 v[240:241], v254 offset:4608
	ds_read_b64_tr_b16 v[242:243], v254 offset:6656
	v_mfma_f32_32x32x16_bf16 v[52:67], v[208:211], v[224:227], v[52:67]
	ds_read_b64_tr_b16 v[220:221], v254 offset:8704
	ds_read_b64_tr_b16 v[222:223], v254 offset:10752
	s_waitcnt lgkmcnt(6)
	v_mfma_f32_32x32x16_bf16 v[52:67], v[202:205], v[228:231], v[52:67]
	ds_read_b64_tr_b16 v[224:225], v254 offset:12800
	ds_read_b64_tr_b16 v[226:227], v254 offset:14848
	v_mfma_f32_32x32x16_bf16 v[52:67], v[212:215], v[232:235], v[52:67]
	ds_read_b64_tr_b16 v[228:229], v254 offset:1024
	ds_read_b64_tr_b16 v[230:231], v254 offset:3072
	s_waitcnt lgkmcnt(6)
	v_mfma_f32_32x32x16_bf16 v[36:51], v[216:219], v[236:239], v[36:51]
	ds_read_b64_tr_b16 v[232:233], v254 offset:5120
	ds_read_b64_tr_b16 v[234:235], v254 offset:7168
	v_mfma_f32_32x32x16_bf16 v[36:51], v[208:211], v[240:243], v[36:51]
	ds_read_b64_tr_b16 v[236:237], v254 offset:9216
	ds_read_b64_tr_b16 v[238:239], v254 offset:11264
	s_waitcnt lgkmcnt(6)
	v_mfma_f32_32x32x16_bf16 v[36:51], v[202:205], v[220:223], v[36:51]
	ds_read_b64_tr_b16 v[240:241], v254 offset:13312
	ds_read_b64_tr_b16 v[242:243], v254 offset:15360
	v_mfma_f32_32x32x16_bf16 v[36:51], v[212:215], v[224:227], v[36:51]
	ds_read_b64_tr_b16 v[220:221], v254 offset:1536
	ds_read_b64_tr_b16 v[222:223], v254 offset:3584
	s_waitcnt lgkmcnt(6)
	v_mfma_f32_32x32x16_bf16 v[20:35], v[216:219], v[228:231], v[20:35]
	ds_read_b64_tr_b16 v[224:225], v254 offset:5632
	ds_read_b64_tr_b16 v[226:227], v254 offset:7680
	v_mfma_f32_32x32x16_bf16 v[20:35], v[208:211], v[232:235], v[20:35]
	ds_read_b64_tr_b16 v[228:229], v254 offset:9728
	ds_read_b64_tr_b16 v[230:231], v254 offset:11776
	s_waitcnt lgkmcnt(6)
	v_mfma_f32_32x32x16_bf16 v[20:35], v[202:205], v[236:239], v[20:35]
	ds_read_b64_tr_b16 v[232:233], v254 offset:13824
	ds_read_b64_tr_b16 v[234:235], v254 offset:15872
	v_mfma_f32_32x32x16_bf16 v[20:35], v[212:215], v[240:243], v[20:35]
	s_waitcnt lgkmcnt(4)
	v_mfma_f32_32x32x16_bf16 v[4:19], v[216:219], v[220:223], v[4:19]
	s_waitcnt vmcnt(4)
	v_mfma_f32_32x32x16_bf16 v[4:19], v[208:211], v[224:227], v[4:19]
	s_waitcnt lgkmcnt(0)
	v_mfma_f32_32x32x16_bf16 v[4:19], v[202:205], v[228:231], v[4:19]
	v_mfma_f32_32x32x16_bf16 v[4:19], v[212:215], v[232:235], v[4:19]
	s_setprio 0
	s_barrier
	s_lshl_b32 s92, s66, 14
	s_add_i32 s95, s92, 0
	v_add_u32_e32 v203, s95, v184
	ds_write_b128 v203, v[136:139]
	v_add_u32_e32 v136, s95, v186
	ds_write_b128 v136, v[132:135]
	v_add_u32_e32 v132, s95, v187
	ds_write_b128 v132, v[144:147] offset:49152
	v_add_u32_e32 v132, s95, v188
	s_waitcnt vmcnt(4)
	ds_write_b128 v132, v[140:143] offset:49152
	v_max_f32_e32 v2, v85, v85
	v_max_f32_e32 v202, v84, v84
	v_max_f32_e32 v2, v202, v2
	v_max3_f32 v2, v2, v86, v87
	v_max3_f32 v2, v2, v88, v89
	v_max3_f32 v2, v2, v90, v91
	v_max3_f32 v2, v2, v92, v93
	v_max3_f32 v2, v2, v94, v95
	v_max3_f32 v2, v2, v96, v97
	v_max3_f32 v2, v2, v98, v99
	v_max3_f32 v2, v2, v68, v69
	v_max3_f32 v2, v2, v70, v71
	v_max3_f32 v2, v2, v72, v73
	v_max3_f32 v2, v2, v74, v75
	v_max3_f32 v2, v2, v76, v77
	v_max3_f32 v2, v2, v78, v79
	v_max3_f32 v2, v2, v80, v81
	v_max3_f32 v2, v2, v82, v83
	v_mov_b32_e32 v202, v2
	s_nop 1
	v_permlane32_swap_b32_e32 v2, v202
	v_max_f32_e32 v202, v202, v202
	v_max_f32_e32 v2, v2, v2
	v_max_f32_e32 v2, v2, v202
	v_sub_f32_e32 v202, v2, v166
	v_cmp_ge_f32_e32 vcc, s74, v202
	v_max_f32_e32 v202, v166, v166
	v_max_f32_e32 v2, v202, v2
	v_sub_f32_e32 v202, v166, v2
	s_cmp_eq_u64 vcc, exec
	v_mul_f32_e32 v202, 0x3e0293ee, v202
	s_cselect_b64 s[6:7], -1, 0
	v_exp_f32_e32 v202, v202
	s_nop 0
	v_cndmask_b32_e64 v202, v202, 1.0, s[6:7]
	v_cmp_gt_f32_e32 vcc, 1.0, v202
	s_cbranch_vccz .LBB0_478
	s_and_saveexec_b64 s[66:67], s[4:5]
	ds_write_b32 v183, v202 offset:128
	s_or_b64 exec, exec, s[66:67]
	s_waitcnt lgkmcnt(0)
	v_add_u32_e32 v144, v181, v180
	ds_read_b128 v[132:135], v144 offset:224
	ds_read_b128 v[136:139], v144 offset:192
	ds_read_b128 v[140:143], v144 offset:160
	ds_read_b128 v[144:147], v144 offset:128
	s_waitcnt lgkmcnt(3)
	v_pk_mul_f32 v[64:65], v[64:65], v[132:133]
	s_waitcnt lgkmcnt(2)
	v_pk_mul_f32 v[60:61], v[60:61], v[136:137]
	s_waitcnt lgkmcnt(1)
	v_pk_mul_f32 v[56:57], v[56:57], v[140:141]
	v_pk_mul_f32 v[66:67], v[66:67], v[134:135]
	v_pk_mul_f32 v[62:63], v[62:63], v[138:139]
	v_pk_mul_f32 v[58:59], v[58:59], v[142:143]
	s_waitcnt lgkmcnt(0)
	v_pk_mul_f32 v[54:55], v[54:55], v[146:147]
	v_pk_mul_f32 v[52:53], v[52:53], v[144:145]
	v_pk_mul_f32 v[48:49], v[48:49], v[132:133]
	v_pk_mul_f32 v[44:45], v[44:45], v[136:137]
	v_pk_mul_f32 v[40:41], v[40:41], v[140:141]
	v_pk_mul_f32 v[50:51], v[50:51], v[134:135]
	v_pk_mul_f32 v[46:47], v[46:47], v[138:139]
	v_pk_mul_f32 v[42:43], v[42:43], v[142:143]
	v_pk_mul_f32 v[38:39], v[38:39], v[146:147]
	v_pk_mul_f32 v[36:37], v[36:37], v[144:145]
	v_pk_mul_f32 v[32:33], v[32:33], v[132:133]
	v_pk_mul_f32 v[28:29], v[28:29], v[136:137]
	v_pk_mul_f32 v[24:25], v[24:25], v[140:141]
	v_pk_mul_f32 v[34:35], v[34:35], v[134:135]
	v_pk_mul_f32 v[30:31], v[30:31], v[138:139]
	v_pk_mul_f32 v[26:27], v[26:27], v[142:143]
	v_pk_mul_f32 v[22:23], v[22:23], v[146:147]
	v_pk_mul_f32 v[20:21], v[20:21], v[144:145]
	v_pk_mul_f32 v[16:17], v[16:17], v[132:133]
	v_pk_mul_f32 v[12:13], v[12:13], v[136:137]
	v_pk_mul_f32 v[8:9], v[8:9], v[140:141]
	v_pk_mul_f32 v[18:19], v[18:19], v[134:135]
	v_pk_mul_f32 v[14:15], v[14:15], v[138:139]
	v_pk_mul_f32 v[10:11], v[10:11], v[142:143]
	v_pk_mul_f32 v[6:7], v[6:7], v[146:147]
	v_pk_mul_f32 v[4:5], v[4:5], v[144:145]
; __device__ __forceinline__ void partialSM(f32x16& p0, f32x16& p1, float& m_reg, float& mn, float& alpha) {
;   constexpr float C = SCALE * 1.4426950408889634f;
;   float pmax = p0[0]; for (int r = 1; r < 16; ++r) pmax = fmaxf(pmax, p0[r]); for (int r = 0; r < 16; ++r) pmax = fmaxf(pmax, p1[r]);
;   { auto rr = __builtin_amdgcn_permlane32_swap(__float_as_uint(pmax), __float_as_uint(pmax), false, false);
;     pmax = fmaxf(__uint_as_float(rr[0]), __uint_as_float(rr[1])); }
;   if (__builtin_expect(__all(pmax - m_reg <= THR / SCALE), 1)) { mn = m_reg; alpha = 1.f; }
;   else { mn = fmaxf(m_reg, pmax); alpha = __builtin_amdgcn_exp2f((m_reg - mn) * C); m_reg = mn; }
;   float mnC = -mn * C;
;   for (int r = 0; r < 16; ++r) p0[r] = fmaf(p0[r], C, mnC); for (int r = 0; r < 16; ++r) p1[r] = fmaf(p1[r], C, mnC);
;   for (int r = 0; r < 16; ++r) p0[r] = __builtin_amdgcn_exp2f(p0[r]);
; }
; __device__ __forceinline__ void finishSM(f32x16& p0, f32x16& p1, float alpha, float& l_reg, bf16x8& pa0, bf16x8& pa1, bf16x8& pa2, bf16x8& pa3) {
;   for (int r = 0; r < 16; ++r) p1[r] = __builtin_amdgcn_exp2f(p1[r]);
;   float ps = 0; for (int r = 0; r < 16; ++r) ps += p0[r]; for (int r = 0; r < 16; ++r) ps += p1[r];
;   { auto rr = __builtin_amdgcn_permlane32_swap(__float_as_uint(ps), __float_as_uint(ps), false, false);
;     ps = __uint_as_float(rr[0]) + __uint_as_float(rr[1]); }
;   l_reg = l_reg * alpha + ps;
;     ...
;   PK4(p0, 0, pa0); PK4(p0, 8, pa1); PK4(p1, 0, pa2); PK4(p1, 8, pa3);
;     ...
; }
; __device__ __forceinline__ void qkt(f32x16& p0, f32x16& p1, const u16* Ks, const bf16x8* qr, int r32, int hi) {
;   p0 = f32x16{}; p1 = f32x16{};
;   for (int d0 = 0; d0 < 8; ++d0) { int cb = (d0 * 16 + hi * 8) * 2;
;     bf16x8 b0 = *reinterpret_cast<const bf16x8*>((const char*)Ks + KSWZ(r32, cb));
;     bf16x8 b1 = *reinterpret_cast<const bf16x8*>((const char*)Ks + KSWZ(32 + r32, cb));
;     p0 = __builtin_amdgcn_mfma_f32_32x32x16_bf16(b0, qr[d0], p0, 0, 0, 0);
;     p1 = __builtin_amdgcn_mfma_f32_32x32x16_bf16(b1, qr[d0], p1, 0, 0, 0); }
; }
.LBB0_478:
	v_cndmask_b32_e64 v2, v2, v166, s[6:7]
	v_mul_f32_e32 v140, 0xbe0293ee, v2
	v_fmamk_f32 v93, v93, 0x3e0293ee, v140
	v_exp_f32_e32 v221, v93
	v_fmamk_f32 v84, v84, 0x3e0293ee, v140
	v_fmamk_f32 v85, v85, 0x3e0293ee, v140
	v_fmamk_f32 v86, v86, 0x3e0293ee, v140
	v_fmamk_f32 v87, v87, 0x3e0293ee, v140
	v_fmamk_f32 v88, v88, 0x3e0293ee, v140
	v_fmamk_f32 v89, v89, 0x3e0293ee, v140
	v_fmamk_f32 v90, v90, 0x3e0293ee, v140
	v_fmamk_f32 v91, v91, 0x3e0293ee, v140
	v_fmamk_f32 v92, v92, 0x3e0293ee, v140
	v_fmamk_f32 v94, v94, 0x3e0293ee, v140
	v_fmamk_f32 v95, v95, 0x3e0293ee, v140
	v_fmamk_f32 v96, v96, 0x3e0293ee, v140
	v_fmamk_f32 v97, v97, 0x3e0293ee, v140
	v_fmamk_f32 v98, v98, 0x3e0293ee, v140
	v_fmamk_f32 v99, v99, 0x3e0293ee, v140
	v_fmamk_f32 v141, v68, 0x3e0293ee, v140
	v_fmamk_f32 v142, v69, 0x3e0293ee, v140
	v_fmamk_f32 v143, v70, 0x3e0293ee, v140
	v_fmamk_f32 v144, v71, 0x3e0293ee, v140
	v_fmamk_f32 v145, v72, 0x3e0293ee, v140
	v_fmamk_f32 v146, v73, 0x3e0293ee, v140
	v_fmamk_f32 v147, v74, 0x3e0293ee, v140
	v_fmamk_f32 v166, v75, 0x3e0293ee, v140
	v_fmamk_f32 v203, v76, 0x3e0293ee, v140
	v_fmamk_f32 v204, v77, 0x3e0293ee, v140
	v_fmamk_f32 v205, v78, 0x3e0293ee, v140
	v_fmamk_f32 v206, v79, 0x3e0293ee, v140
	v_fmamk_f32 v207, v80, 0x3e0293ee, v140
	v_fmamk_f32 v208, v81, 0x3e0293ee, v140
	v_fmamk_f32 v209, v82, 0x3e0293ee, v140
	v_fmac_f32_e32 v140, 0x3e0293ee, v83
	v_exp_f32_e32 v210, v84
	v_exp_f32_e32 v211, v85
	v_exp_f32_e32 v212, v86
	v_exp_f32_e32 v213, v87
	v_exp_f32_e32 v214, v88
	v_exp_f32_e32 v215, v89
	v_exp_f32_e32 v216, v90
	v_exp_f32_e32 v217, v91
	v_exp_f32_e32 v218, v92
	v_exp_f32_e32 v222, v94
	v_exp_f32_e32 v223, v95
	v_exp_f32_e32 v224, v96
	v_exp_f32_e32 v225, v97
	v_exp_f32_e32 v226, v98
	v_exp_f32_e32 v227, v99
	s_waitcnt lgkmcnt(0)
	s_barrier
	s_setprio 1
	v_add_u32_e32 v254, s95, v189
	ds_read_b128 v[68:71], v254 offset:49152
	ds_read_b128 v[72:75], v254 offset:49280
	v_add_u32_e32 v254, s95, v190
	ds_read_b128 v[76:79], v254 offset:49152
	ds_read_b128 v[80:83], v254 offset:49280
	v_add_u32_e32 v254, s95, v191
	ds_read_b128 v[228:231], v254 offset:49152
	ds_read_b128 v[232:235], v254 offset:49280
	v_add_u32_e32 v254, s95, v192
	ds_read_b128 v[236:239], v254 offset:49152
	ds_read_b128 v[240:243], v254 offset:49280
	v_add_u32_e32 v254, s95, v189
	ds_read_b128 v[246:249], v254 offset:57344
	ds_read_b128 v[250:253], v254 offset:57472
	s_waitcnt lgkmcnt(9)
	v_mfma_f32_32x32x16_bf16 v[84:99], v[68:71], v[100:103], 0
	s_waitcnt lgkmcnt(8)
	v_mfma_f32_32x32x16_bf16 v[84:99], v[72:75], v[116:119], v[84:99]
	s_waitcnt lgkmcnt(7)
	v_mfma_f32_32x32x16_bf16 v[84:99], v[76:79], v[104:107], v[84:99]
	s_waitcnt lgkmcnt(6)
	v_mfma_f32_32x32x16_bf16 v[84:99], v[80:83], v[120:123], v[84:99]
	s_waitcnt lgkmcnt(5)
	v_mfma_f32_32x32x16_bf16 v[84:99], v[228:231], v[108:111], v[84:99]
	v_add_u32_e32 v254, s95, v190
	ds_read_b128 v[228:231], v254 offset:57344
	s_waitcnt lgkmcnt(5)
	v_mfma_f32_32x32x16_bf16 v[84:99], v[232:235], v[124:127], v[84:99]
	ds_read_b128 v[232:235], v254 offset:57472
	s_waitcnt lgkmcnt(5)
	v_mfma_f32_32x32x16_bf16 v[84:99], v[236:239], v[112:115], v[84:99]
	v_add_u32_e32 v254, s95, v191
	ds_read_b128 v[236:239], v254 offset:57344
	s_waitcnt lgkmcnt(5)
	v_mfma_f32_32x32x16_bf16 v[84:99], v[240:243], v[128:131], v[84:99]
	ds_read_b128 v[240:243], v254 offset:57472
	s_waitcnt lgkmcnt(5)
	v_mfma_f32_32x32x16_bf16 v[68:83], v[246:249], v[100:103], 0
	v_add_u32_e32 v254, s95, v192
	ds_read_b128 v[246:249], v254 offset:57344
	s_waitcnt lgkmcnt(5)
	v_mfma_f32_32x32x16_bf16 v[68:83], v[250:253], v[116:119], v[68:83]
	ds_read_b128 v[250:253], v254 offset:57472
	s_waitcnt lgkmcnt(5)
	v_mfma_f32_32x32x16_bf16 v[68:83], v[228:231], v[104:107], v[68:83]
	s_waitcnt lgkmcnt(4)
	v_mfma_f32_32x32x16_bf16 v[68:83], v[232:235], v[120:123], v[68:83]
	s_waitcnt lgkmcnt(3)
	v_mfma_f32_32x32x16_bf16 v[68:83], v[236:239], v[108:111], v[68:83]
	s_waitcnt lgkmcnt(2)
	v_mfma_f32_32x32x16_bf16 v[68:83], v[240:243], v[124:127], v[68:83]
	s_waitcnt lgkmcnt(1)
	v_mfma_f32_32x32x16_bf16 v[68:83], v[246:249], v[112:115], v[68:83]
	s_waitcnt lgkmcnt(0)
	v_mfma_f32_32x32x16_bf16 v[68:83], v[250:253], v[128:131], v[68:83]
	s_setprio 0
	s_barrier
	v_exp_f32_e32 v140, v140
	v_exp_f32_e32 v139, v166
	v_add_f32_e32 v166, 0, v210
	v_add_f32_e32 v166, v211, v166
	v_add_f32_e32 v166, v212, v166
	v_add_f32_e32 v166, v213, v166
	v_add_f32_e32 v166, v214, v166
	v_add_f32_e32 v166, v215, v166
	v_add_f32_e32 v166, v216, v166
	v_add_f32_e32 v166, v217, v166
	v_add_f32_e32 v166, v218, v166
	v_add_f32_e32 v166, v221, v166
	v_add_f32_e32 v166, v222, v166
	v_add_f32_e32 v166, v223, v166
	v_exp_f32_e32 v132, v141
	v_add_f32_e32 v166, v224, v166
	v_exp_f32_e32 v133, v142
	v_add_f32_e32 v166, v225, v166
	v_exp_f32_e32 v134, v143
	v_add_f32_e32 v166, v226, v166
	v_exp_f32_e32 v135, v144
	v_add_f32_e32 v166, v227, v166
	v_exp_f32_e32 v136, v145
	v_add_f32_e32 v166, v132, v166
	v_exp_f32_e32 v137, v146
	v_add_f32_e32 v166, v133, v166
	v_exp_f32_e32 v138, v147
	v_add_f32_e32 v166, v134, v166
	v_add_f32_e32 v166, v135, v166
	v_exp_f32_e32 v141, v203
	v_add_f32_e32 v166, v136, v166
	v_exp_f32_e32 v142, v204
	v_add_f32_e32 v166, v137, v166
	v_exp_f32_e32 v143, v205
	v_add_f32_e32 v166, v138, v166
	v_exp_f32_e32 v144, v206
	v_add_f32_e32 v166, v139, v166
	v_exp_f32_e32 v145, v207
	v_add_f32_e32 v166, v141, v166
	v_exp_f32_e32 v146, v208
	v_add_f32_e32 v166, v142, v166
	v_exp_f32_e32 v147, v209
	v_add_f32_e32 v166, v143, v166
	v_add_f32_e32 v166, v144, v166
	v_add_f32_e32 v166, v145, v166
	v_add_f32_e32 v166, v146, v166
	v_add_f32_e32 v166, v147, v166
	v_add_f32_e32 v219, v140, v166
	v_mov_b32_e32 v220, v219
	s_nop 1
	v_permlane32_swap_b32_e32 v219, v220
	v_cvt_pk_bf16_f32 v204, v210, v211
	v_cvt_pk_bf16_f32 v205, v212, v213
	v_cvt_pk_bf16_f32 v206, v214, v215
	v_cvt_pk_bf16_f32 v207, v216, v217
	v_cvt_pk_bf16_f32 v208, v218, v221
	v_cvt_pk_bf16_f32 v209, v222, v223
	v_cvt_pk_bf16_f32 v210, v224, v225
	v_cvt_pk_bf16_f32 v211, v226, v227
	v_cvt_pk_bf16_f32 v212, v132, v133
	v_cvt_pk_bf16_f32 v213, v134, v135
	v_cvt_pk_bf16_f32 v214, v136, v137
	v_cvt_pk_bf16_f32 v215, v138, v139
	v_cvt_pk_bf16_f32 v222, v141, v142
	v_cvt_pk_bf16_f32 v223, v143, v144
	v_cvt_pk_bf16_f32 v224, v145, v146
	v_cvt_pk_bf16_f32 v225, v147, v140
	s_nop 0
	v_permlane32_swap_b32_e32 v204, v206
	v_permlane32_swap_b32_e32 v205, v207
	v_permlane32_swap_b32_e32 v208, v210
	v_permlane32_swap_b32_e32 v209, v211
	v_permlane32_swap_b32_e32 v212, v214
	v_permlane32_swap_b32_e32 v213, v215
	v_permlane32_swap_b32_e32 v222, v224
	v_permlane32_swap_b32_e32 v223, v225
	s_min_u32 s7, s16, s90
	s_add_i32 s7, s7, s88
	s_lshl_b32 s7, s7, 6
	v_add_u32_e32 v244, s7, v167
	v_add_u32_e32 v245, s7, v185
	v_lshl_or_b32 v244, v244, 8, v182
	v_lshl_or_b32 v245, v245, 8, v182
	global_load_dwordx4 v[136:139], v244, s[58:59]
	global_load_dwordx4 v[132:135], v245, s[58:59]
	global_load_dwordx4 v[144:147], v244, s[64:65]
	global_load_dwordx4 v[140:143], v245, s[64:65]
	s_barrier
; #define SBAR() __builtin_amdgcn_sched_barrier(0)
; __device__ __forceinline__ void partialSM(f32x16& p0, f32x16& p1, float& m_reg, float& mn, float& alpha) {
;   constexpr float C = SCALE * 1.4426950408889634f;
;   float pmax = p0[0]; for (int r = 1; r < 16; ++r) pmax = fmaxf(pmax, p0[r]); for (int r = 0; r < 16; ++r) pmax = fmaxf(pmax, p1[r]);
;   { auto rr = __builtin_amdgcn_permlane32_swap(__float_as_uint(pmax), __float_as_uint(pmax), false, false);
;     pmax = fmaxf(__uint_as_float(rr[0]), __uint_as_float(rr[1])); }
;   if (__builtin_expect(__all(pmax - m_reg <= THR / SCALE), 1)) { mn = m_reg; alpha = 1.f; }
;   else { mn = fmaxf(m_reg, pmax); alpha = __builtin_amdgcn_exp2f((m_reg - mn) * C); m_reg = mn; }
; template <int OFF> __device__ __forceinline__ s16x4 tr_read(int vb) {
;   s16x4 r; asm volatile("ds_read_b64_tr_b16 %0, %1 offset:%2" : "=&v"(r) : "v"(vb), "i"(OFF) : "memory"); return r;
; }
; template <int D0> __device__ __forceinline__ void pv_one(f32x16& od, int vb, bf16x8 pa0, bf16x8 pa1, bf16x8 pa2, bf16x8 pa3) {
;   const s16x4 l0 = tr_read<v_rd_off(D0, 0, 0)>(vb), h0 = tr_read<v_rd_off(D0, 0, 1)>(vb), l1 = tr_read<v_rd_off(D0, 1, 0)>(vb), h1 = tr_read<v_rd_off(D0, 1, 1)>(vb);
;   const s16x4 l2 = tr_read<v_rd_off(D0, 2, 0)>(vb), h2 = tr_read<v_rd_off(D0, 2, 1)>(vb), l3 = tr_read<v_rd_off(D0, 3, 0)>(vb), h3 = tr_read<v_rd_off(D0, 3, 1)>(vb);
;   asm volatile("s_waitcnt lgkmcnt(0)" ::: "memory"); SBAR();
;     ...
;   od = __builtin_amdgcn_mfma_f32_32x32x16_bf16(pa0, PK(l0, h0), od, 0, 0, 0);
;   od = __builtin_amdgcn_mfma_f32_32x32x16_bf16(pa1, PK(l1, h1), od, 0, 0, 0);
;   od = __builtin_amdgcn_mfma_f32_32x32x16_bf16(pa2, PK(l2, h2), od, 0, 0, 0);
;   od = __builtin_amdgcn_mfma_f32_32x32x16_bf16(pa3, PK(l3, h3), od, 0, 0, 0);
;     ...
; }
; __device__ __forceinline__ void pv_d0(f32x16* o, int vb, bf16x8 pa0, bf16x8 pa1, bf16x8 pa2, bf16x8 pa3) {
;   pv_one<0>(o[0], vb, pa0, pa1, pa2, pa3); pv_one<1>(o[1], vb, pa0, pa1, pa2, pa3); pv_one<2>(o[2], vb, pa0, pa1, pa2, pa3); pv_one<3>(o[3], vb, pa0, pa1, pa2, pa3);
	s_setprio 1
	v_add_u32_e32 v254, s93, v197
	ds_read_b64_tr_b16 v[230:231], v254 offset:0
	ds_read_b64_tr_b16 v[232:233], v254 offset:2048
	ds_read_b64_tr_b16 v[234:235], v254 offset:4096
	ds_read_b64_tr_b16 v[236:237], v254 offset:6144
	ds_read_b64_tr_b16 v[238:239], v254 offset:8192
	ds_read_b64_tr_b16 v[240:241], v254 offset:10240
	ds_read_b64_tr_b16 v[242:243], v254 offset:12288
	ds_read_b64_tr_b16 v[244:245], v254 offset:14336
	ds_read_b64_tr_b16 v[246:247], v254 offset:512
	ds_read_b64_tr_b16 v[248:249], v254 offset:2560
	s_waitcnt lgkmcnt(6)
	v_mfma_f32_32x32x16_bf16 v[52:67], v[204:207], v[230:233], v[52:67]
	ds_read_b64_tr_b16 v[250:251], v254 offset:4608
	ds_read_b64_tr_b16 v[252:253], v254 offset:6656
	v_mfma_f32_32x32x16_bf16 v[52:67], v[208:211], v[234:237], v[52:67]
	ds_read_b64_tr_b16 v[230:231], v254 offset:8704
	ds_read_b64_tr_b16 v[232:233], v254 offset:10752
	s_waitcnt lgkmcnt(6)
	v_mfma_f32_32x32x16_bf16 v[52:67], v[212:215], v[238:241], v[52:67]
	ds_read_b64_tr_b16 v[234:235], v254 offset:12800
	ds_read_b64_tr_b16 v[236:237], v254 offset:14848
	v_mfma_f32_32x32x16_bf16 v[52:67], v[222:225], v[242:245], v[52:67]
	ds_read_b64_tr_b16 v[238:239], v254 offset:1024
	ds_read_b64_tr_b16 v[240:241], v254 offset:3072
	s_waitcnt lgkmcnt(6)
	v_mfma_f32_32x32x16_bf16 v[36:51], v[204:207], v[246:249], v[36:51]
	ds_read_b64_tr_b16 v[242:243], v254 offset:5120
	ds_read_b64_tr_b16 v[244:245], v254 offset:7168
	v_mfma_f32_32x32x16_bf16 v[36:51], v[208:211], v[250:253], v[36:51]
	ds_read_b64_tr_b16 v[246:247], v254 offset:9216
	ds_read_b64_tr_b16 v[248:249], v254 offset:11264
	s_waitcnt lgkmcnt(6)
	v_mfma_f32_32x32x16_bf16 v[36:51], v[212:215], v[230:233], v[36:51]
	ds_read_b64_tr_b16 v[250:251], v254 offset:13312
	ds_read_b64_tr_b16 v[252:253], v254 offset:15360
	v_mfma_f32_32x32x16_bf16 v[36:51], v[222:225], v[234:237], v[36:51]
	ds_read_b64_tr_b16 v[230:231], v254 offset:1536
	ds_read_b64_tr_b16 v[232:233], v254 offset:3584
	s_waitcnt lgkmcnt(6)
	v_mfma_f32_32x32x16_bf16 v[20:35], v[204:207], v[238:241], v[20:35]
	ds_read_b64_tr_b16 v[234:235], v254 offset:5632
	ds_read_b64_tr_b16 v[236:237], v254 offset:7680
	v_mfma_f32_32x32x16_bf16 v[20:35], v[208:211], v[242:245], v[20:35]
	ds_read_b64_tr_b16 v[238:239], v254 offset:9728
	ds_read_b64_tr_b16 v[240:241], v254 offset:11776
	s_waitcnt lgkmcnt(6)
	v_mfma_f32_32x32x16_bf16 v[20:35], v[212:215], v[246:249], v[20:35]
	ds_read_b64_tr_b16 v[242:243], v254 offset:13824
	ds_read_b64_tr_b16 v[244:245], v254 offset:15872
	v_mfma_f32_32x32x16_bf16 v[20:35], v[222:225], v[250:253], v[20:35]
	s_waitcnt lgkmcnt(4)
	v_mfma_f32_32x32x16_bf16 v[4:19], v[204:207], v[230:233], v[4:19]
	v_mfma_f32_32x32x16_bf16 v[4:19], v[208:211], v[234:237], v[4:19]
	s_waitcnt lgkmcnt(0)
	v_mfma_f32_32x32x16_bf16 v[4:19], v[212:215], v[238:241], v[4:19]
	v_mfma_f32_32x32x16_bf16 v[4:19], v[222:225], v[242:245], v[4:19]
	s_setprio 0
	s_barrier
	s_add_i32 s30, s94, 0
	v_add_u32_e32 v203, s30, v184
	s_waitcnt vmcnt(4)
	ds_write_b128 v203, v[152:155]
	v_add_u32_e32 v152, s30, v186
	ds_write_b128 v152, v[148:151]
	v_add_u32_e32 v148, s30, v187
	ds_write_b128 v148, v[160:163] offset:49152
	v_add_u32_e32 v148, s30, v188
	s_waitcnt vmcnt(4)
	ds_write_b128 v148, v[156:159] offset:49152
	v_max_f32_e32 v166, v85, v85
	v_max_f32_e32 v203, v84, v84
	v_max_f32_e32 v166, v203, v166
	v_max3_f32 v166, v166, v86, v87
	v_max3_f32 v166, v166, v88, v89
	v_max3_f32 v166, v166, v90, v91
	v_max3_f32 v166, v166, v92, v93
	v_max3_f32 v166, v166, v94, v95
	v_max3_f32 v166, v166, v96, v97
	v_max3_f32 v166, v166, v98, v99
	v_max3_f32 v166, v166, v68, v69
	v_max3_f32 v166, v166, v70, v71
	v_max3_f32 v166, v166, v72, v73
	v_max3_f32 v166, v166, v74, v75
	v_max3_f32 v166, v166, v76, v77
	v_max3_f32 v166, v166, v78, v79
	v_max3_f32 v166, v166, v80, v81
	v_max3_f32 v166, v166, v82, v83
	v_mov_b32_e32 v203, v166
	s_nop 1
	v_permlane32_swap_b32_e32 v166, v203
	v_max_f32_e32 v203, v203, v203
	v_max_f32_e32 v166, v166, v166
	v_max_f32_e32 v166, v166, v203
	v_sub_f32_e32 v203, v166, v2
	v_cmp_ge_f32_e32 vcc, s74, v203
	v_max_f32_e32 v203, v2, v2
	v_max_f32_e32 v166, v203, v166
	v_sub_f32_e32 v203, v2, v166
	v_mul_f32_e32 v203, 0x3e0293ee, v203
	v_exp_f32_e32 v203, v203
	s_cmp_eq_u64 vcc, exec
	s_cselect_b64 s[6:7], -1, 0
	v_cndmask_b32_e64 v221, v203, 1.0, s[6:7]
	v_cmp_gt_f32_e32 vcc, 1.0, v221
	s_cbranch_vccz .LBB0_482
	s_and_saveexec_b64 s[66:67], s[4:5]
	ds_write_b32 v183, v221 offset:128
	s_or_b64 exec, exec, s[66:67]
	s_waitcnt lgkmcnt(0)
	v_add_u32_e32 v160, v181, v180
	ds_read_b128 v[148:151], v160 offset:224
	ds_read_b128 v[152:155], v160 offset:192
	ds_read_b128 v[156:159], v160 offset:160
	ds_read_b128 v[160:163], v160 offset:128
	s_waitcnt lgkmcnt(3)
	v_pk_mul_f32 v[64:65], v[64:65], v[148:149]
	s_waitcnt lgkmcnt(2)
	v_pk_mul_f32 v[60:61], v[60:61], v[152:153]
	s_waitcnt lgkmcnt(1)
	v_pk_mul_f32 v[56:57], v[56:57], v[156:157]
	v_pk_mul_f32 v[66:67], v[66:67], v[150:151]
	v_pk_mul_f32 v[62:63], v[62:63], v[154:155]
	v_pk_mul_f32 v[58:59], v[58:59], v[158:159]
	s_waitcnt lgkmcnt(0)
	v_pk_mul_f32 v[54:55], v[54:55], v[162:163]
	v_pk_mul_f32 v[52:53], v[52:53], v[160:161]
	v_pk_mul_f32 v[48:49], v[48:49], v[148:149]
	v_pk_mul_f32 v[44:45], v[44:45], v[152:153]
	v_pk_mul_f32 v[40:41], v[40:41], v[156:157]
	v_pk_mul_f32 v[50:51], v[50:51], v[150:151]
	v_pk_mul_f32 v[46:47], v[46:47], v[154:155]
	v_pk_mul_f32 v[42:43], v[42:43], v[158:159]
	v_pk_mul_f32 v[38:39], v[38:39], v[162:163]
	v_pk_mul_f32 v[36:37], v[36:37], v[160:161]
	v_pk_mul_f32 v[32:33], v[32:33], v[148:149]
	v_pk_mul_f32 v[28:29], v[28:29], v[152:153]
	v_pk_mul_f32 v[24:25], v[24:25], v[156:157]
	v_pk_mul_f32 v[34:35], v[34:35], v[150:151]
	v_pk_mul_f32 v[30:31], v[30:31], v[154:155]
	v_pk_mul_f32 v[26:27], v[26:27], v[158:159]
	v_pk_mul_f32 v[22:23], v[22:23], v[162:163]
	v_pk_mul_f32 v[20:21], v[20:21], v[160:161]
	v_pk_mul_f32 v[16:17], v[16:17], v[148:149]
	v_pk_mul_f32 v[12:13], v[12:13], v[152:153]
	v_pk_mul_f32 v[8:9], v[8:9], v[156:157]
	v_pk_mul_f32 v[18:19], v[18:19], v[150:151]
	v_pk_mul_f32 v[14:15], v[14:15], v[154:155]
	v_pk_mul_f32 v[10:11], v[10:11], v[158:159]
	v_pk_mul_f32 v[6:7], v[6:7], v[162:163]
	v_pk_mul_f32 v[4:5], v[4:5], v[160:161]

; #define SBAR() __builtin_amdgcn_sched_barrier(0)
; #define QKT(P0, P1, KS) do { if (MODE == 1) qkt_lds(P0, P1, KS, qs, r32, hi); else qkt(P0, P1, KS, qr, r32, hi); } while (0)
; __device__ __forceinline__ void finishSM(f32x16& p0, f32x16& p1, float alpha, float& l_reg, bf16x8& pa0, bf16x8& pa1, bf16x8& pa2, bf16x8& pa3) {
;   for (int r = 0; r < 16; ++r) p1[r] = __builtin_amdgcn_exp2f(p1[r]);
;   float ps = 0; for (int r = 0; r < 16; ++r) ps += p0[r]; for (int r = 0; r < 16; ++r) ps += p1[r];
;   { auto rr = __builtin_amdgcn_permlane32_swap(__float_as_uint(ps), __float_as_uint(ps), false, false);
;     ps = __uint_as_float(rr[0]) + __uint_as_float(rr[1]); }
;   l_reg = l_reg * alpha + ps;
;     ...
;   PK4(p0, 0, pa0); PK4(p0, 8, pa1); PK4(p1, 0, pa2); PK4(p1, 8, pa3);
;     ...
; }
; __device__ __forceinline__ void qkt(f32x16& p0, f32x16& p1, const u16* Ks, const bf16x8* qr, int r32, int hi) {
;   p0 = f32x16{}; p1 = f32x16{};
;   for (int d0 = 0; d0 < 8; ++d0) { int cb = (d0 * 16 + hi * 8) * 2;
;     bf16x8 b0 = *reinterpret_cast<const bf16x8*>((const char*)Ks + KSWZ(r32, cb));
;     bf16x8 b1 = *reinterpret_cast<const bf16x8*>((const char*)Ks + KSWZ(32 + r32, cb));
;     p0 = __builtin_amdgcn_mfma_f32_32x32x16_bf16(b0, qr[d0], p0, 0, 0, 0);
;     p1 = __builtin_amdgcn_mfma_f32_32x32x16_bf16(b1, qr[d0], p1, 0, 0, 0); }
; }
; template <int MODE> ...
;     ...
;     for (int j = 1; j + 1 < NT; j += 2) {
;       const int s0_ = sj, s1_ = sj == 2 ? 0 : sj + 1, s2_ = s1_ == 2 ? 0 : s1_ + 1;
;       SBAR(); QKT(pB0, pB1, (u16*)((char*)K_lds + s0_ * SHM_K));
;       finishSM(pA0, pA1, alA, l_reg, pa0, pa1, pa2, pa3); SBAR();
;       { const int tn = (j + 2 < NT) ? j + 2 : NT - 1; SLOAD(SO, tn); } SBAR();
.Lstg_loop:
	s_barrier
	s_add_i32 s7, s89, 1
	s_cmp_lg_u32 s89, 2
	s_cselect_b32 s66, s7, 0
	s_add_i32 s7, s66, 1
	s_cmp_lg_u32 s66, 2
	s_mov_b32 s6, s89
	s_cselect_b32 s89, s7, 0
	s_lshl_b32 s93, s6, 14
	s_add_i32 s6, s93, 0
	s_setprio 1
	v_add_u32_e32 v254, s6, v189
	ds_read_b128 v[68:71], v254 offset:49152
	ds_read_b128 v[72:75], v254 offset:49280
	v_add_u32_e32 v254, s6, v190
	ds_read_b128 v[76:79], v254 offset:49152
	ds_read_b128 v[80:83], v254 offset:49280
	v_add_u32_e32 v254, s6, v191
	ds_read_b128 v[220:223], v254 offset:49152
	ds_read_b128 v[224:227], v254 offset:49280
	v_add_u32_e32 v254, s6, v192
	ds_read_b128 v[228:231], v254 offset:49152
	ds_read_b128 v[232:235], v254 offset:49280
	v_add_u32_e32 v254, s6, v189
	ds_read_b128 v[236:239], v254 offset:57344
	ds_read_b128 v[240:243], v254 offset:57472
	s_waitcnt lgkmcnt(9)
	v_mfma_f32_32x32x16_bf16 v[84:99], v[68:71], v[100:103], 0
	s_waitcnt lgkmcnt(8)
	v_mfma_f32_32x32x16_bf16 v[84:99], v[72:75], v[116:119], v[84:99]
	s_waitcnt lgkmcnt(7)
	v_mfma_f32_32x32x16_bf16 v[84:99], v[76:79], v[104:107], v[84:99]
	s_waitcnt lgkmcnt(6)
	v_mfma_f32_32x32x16_bf16 v[84:99], v[80:83], v[120:123], v[84:99]
	s_waitcnt lgkmcnt(5)
	v_mfma_f32_32x32x16_bf16 v[84:99], v[220:223], v[108:111], v[84:99]
	v_add_u32_e32 v254, s6, v190
	ds_read_b128 v[220:223], v254 offset:57344
	s_waitcnt lgkmcnt(5)
	v_mfma_f32_32x32x16_bf16 v[84:99], v[224:227], v[124:127], v[84:99]
	ds_read_b128 v[224:227], v254 offset:57472
	s_waitcnt lgkmcnt(5)
	v_mfma_f32_32x32x16_bf16 v[84:99], v[228:231], v[112:115], v[84:99]
	v_add_u32_e32 v254, s6, v191
	ds_read_b128 v[228:231], v254 offset:57344
	s_waitcnt lgkmcnt(5)
	v_mfma_f32_32x32x16_bf16 v[84:99], v[232:235], v[128:131], v[84:99]
	ds_read_b128 v[232:235], v254 offset:57472
	s_waitcnt lgkmcnt(5)
	v_mfma_f32_32x32x16_bf16 v[68:83], v[236:239], v[100:103], 0
	v_add_u32_e32 v254, s6, v192
	ds_read_b128 v[236:239], v254 offset:57344
	s_waitcnt lgkmcnt(5)
	v_mfma_f32_32x32x16_bf16 v[68:83], v[240:243], v[116:119], v[68:83]
	ds_read_b128 v[240:243], v254 offset:57472
	s_waitcnt lgkmcnt(5)
	v_mfma_f32_32x32x16_bf16 v[68:83], v[220:223], v[104:107], v[68:83]
	s_waitcnt lgkmcnt(4)
	v_mfma_f32_32x32x16_bf16 v[68:83], v[224:227], v[120:123], v[68:83]
	s_waitcnt lgkmcnt(3)
	v_mfma_f32_32x32x16_bf16 v[68:83], v[228:231], v[108:111], v[68:83]
	s_waitcnt lgkmcnt(2)
	v_mfma_f32_32x32x16_bf16 v[68:83], v[232:235], v[124:127], v[68:83]
	s_waitcnt lgkmcnt(1)
	v_mfma_f32_32x32x16_bf16 v[68:83], v[236:239], v[112:115], v[68:83]
	s_waitcnt lgkmcnt(0)
	v_mfma_f32_32x32x16_bf16 v[68:83], v[240:243], v[128:131], v[68:83]
	s_setprio 0
	s_barrier
	v_exp_f32_e32 v160, v160
	v_exp_f32_e32 v161, v161
	v_exp_f32_e32 v158, v158
	v_exp_f32_e32 v159, v159
	v_exp_f32_e32 v156, v156
	v_exp_f32_e32 v157, v157
	v_exp_f32_e32 v154, v154
	v_exp_f32_e32 v155, v155
	v_exp_f32_e32 v152, v152
	v_exp_f32_e32 v153, v153
	v_exp_f32_e32 v150, v150
	v_exp_f32_e32 v151, v151
	v_exp_f32_e32 v148, v148
	v_exp_f32_e32 v149, v149
	v_exp_f32_e32 v2, v162
	v_exp_f32_e32 v162, v163
	v_add_f32_e32 v163, 0, v216
	v_add_f32_e32 v163, v218, v163
	v_add_f32_e32 v163, v214, v163
	v_add_f32_e32 v163, v217, v163
	v_add_f32_e32 v163, v213, v163
	v_add_f32_e32 v163, v215, v163
	v_add_f32_e32 v163, v211, v163
	v_add_f32_e32 v163, v212, v163
	v_add_f32_e32 v163, v208, v163
	v_add_f32_e32 v163, v210, v163
	v_add_f32_e32 v163, v207, v163
	v_add_f32_e32 v163, v209, v163
	v_add_f32_e32 v163, v204, v163
	v_add_f32_e32 v163, v206, v163
	v_add_f32_e32 v163, v203, v163
	v_add_f32_e32 v163, v205, v163
	v_add_f32_e32 v163, v2, v163
	v_add_f32_e32 v163, v162, v163
	v_add_f32_e32 v163, v160, v163
	v_add_f32_e32 v163, v161, v163
	v_add_f32_e32 v163, v158, v163
	v_add_f32_e32 v163, v159, v163
	v_add_f32_e32 v163, v156, v163
	v_add_f32_e32 v163, v157, v163
	v_add_f32_e32 v163, v154, v163
	v_add_f32_e32 v163, v155, v163
	v_add_f32_e32 v163, v152, v163
	v_add_f32_e32 v163, v153, v163
	v_add_f32_e32 v163, v150, v163
	v_add_f32_e32 v163, v151, v163
	v_add_f32_e32 v163, v148, v163
	v_add_f32_e32 v200, v149, v163
	v_mov_b32_e32 v201, v200
	v_cvt_pk_bf16_f32 v216, v216, v218
	v_cvt_pk_bf16_f32 v217, v214, v217
	v_cvt_pk_bf16_f32 v218, v213, v215
	v_cvt_pk_bf16_f32 v219, v211, v212
	v_cvt_pk_bf16_f32 v208, v208, v210
	v_cvt_pk_bf16_f32 v209, v207, v209
	v_cvt_pk_bf16_f32 v210, v204, v206
	v_cvt_pk_bf16_f32 v211, v203, v205
	v_cvt_pk_bf16_f32 v202, v2, v162
	v_cvt_pk_bf16_f32 v203, v160, v161
	v_cvt_pk_bf16_f32 v204, v158, v159
	v_permlane32_swap_b32_e32 v200, v201
	v_cvt_pk_bf16_f32 v205, v156, v157
	v_permlane32_swap_b32_e32 v202, v204
	v_cvt_pk_bf16_f32 v212, v154, v155
	v_cvt_pk_bf16_f32 v213, v152, v153
	v_cvt_pk_bf16_f32 v214, v150, v151
	v_cvt_pk_bf16_f32 v215, v148, v149
	v_permlane32_swap_b32_e32 v216, v218
	v_permlane32_swap_b32_e32 v217, v219
	v_permlane32_swap_b32_e32 v208, v210
	v_permlane32_swap_b32_e32 v209, v211
	v_permlane32_swap_b32_e32 v203, v205
	v_permlane32_swap_b32_e32 v212, v214
	v_permlane32_swap_b32_e32 v213, v215
	s_add_i32 s91, s16, -1
	s_min_u32 s7, s91, s90
	s_add_i32 s7, s7, s88
	s_lshl_b32 s7, s7, 6
	v_add_u32_e32 v244, s7, v167
	v_add_u32_e32 v245, s7, v185
	v_lshl_or_b32 v244, v244, 8, v182
	v_lshl_or_b32 v245, v245, 8, v182
	global_load_dwordx4 v[152:155], v244, s[58:59]
	global_load_dwordx4 v[148:151], v245, s[58:59]
	global_load_dwordx4 v[160:163], v244, s[64:65]
	global_load_dwordx4 v[156:159], v245, s[64:65]
	s_lshl_b32 s94, s89, 14
	s_barrier
; #define SBAR() __builtin_amdgcn_sched_barrier(0)
; __device__ __forceinline__ void partialSM(f32x16& p0, f32x16& p1, float& m_reg, float& mn, float& alpha) {
;   constexpr float C = SCALE * 1.4426950408889634f;
;   float pmax = p0[0]; for (int r = 1; r < 16; ++r) pmax = fmaxf(pmax, p0[r]); for (int r = 0; r < 16; ++r) pmax = fmaxf(pmax, p1[r]);
;   { auto rr = __builtin_amdgcn_permlane32_swap(__float_as_uint(pmax), __float_as_uint(pmax), false, false);
;     pmax = fmaxf(__uint_as_float(rr[0]), __uint_as_float(rr[1])); }
;   if (__builtin_expect(__all(pmax - m_reg <= THR / SCALE), 1)) { mn = m_reg; alpha = 1.f; }
;   else { mn = fmaxf(m_reg, pmax); alpha = __builtin_amdgcn_exp2f((m_reg - mn) * C); m_reg = mn; }
; template <int OFF> __device__ __forceinline__ s16x4 tr_read(int vb) {
;   s16x4 r; asm volatile("ds_read_b64_tr_b16 %0, %1 offset:%2" : "=&v"(r) : "v"(vb), "i"(OFF) : "memory"); return r;
; }
; template <int D0> __device__ __forceinline__ void pv_one(f32x16& od, int vb, bf16x8 pa0, bf16x8 pa1, bf16x8 pa2, bf16x8 pa3) {
;   const s16x4 l0 = tr_read<v_rd_off(D0, 0, 0)>(vb), h0 = tr_read<v_rd_off(D0, 0, 1)>(vb), l1 = tr_read<v_rd_off(D0, 1, 0)>(vb), h1 = tr_read<v_rd_off(D0, 1, 1)>(vb);
;   const s16x4 l2 = tr_read<v_rd_off(D0, 2, 0)>(vb), h2 = tr_read<v_rd_off(D0, 2, 1)>(vb), l3 = tr_read<v_rd_off(D0, 3, 0)>(vb), h3 = tr_read<v_rd_off(D0, 3, 1)>(vb);
;   asm volatile("s_waitcnt lgkmcnt(0)" ::: "memory"); SBAR();
;     ...
;   od = __builtin_amdgcn_mfma_f32_32x32x16_bf16(pa0, PK(l0, h0), od, 0, 0, 0);
;   od = __builtin_amdgcn_mfma_f32_32x32x16_bf16(pa1, PK(l1, h1), od, 0, 0, 0);
;   od = __builtin_amdgcn_mfma_f32_32x32x16_bf16(pa2, PK(l2, h2), od, 0, 0, 0);
;   od = __builtin_amdgcn_mfma_f32_32x32x16_bf16(pa3, PK(l3, h3), od, 0, 0, 0);
;     ...
; }
; __device__ __forceinline__ void pv_d0(f32x16* o, int vb, bf16x8 pa0, bf16x8 pa1, bf16x8 pa2, bf16x8 pa3) {
;   pv_one<0>(o[0], vb, pa0, pa1, pa2, pa3); pv_one<1>(o[1], vb, pa0, pa1, pa2, pa3); pv_one<2>(o[2], vb, pa0, pa1, pa2, pa3); pv_one<3>(o[3], vb, pa0, pa1, pa2, pa3);
	s_setprio 1
	v_add_u32_e32 v254, s94, v197
	ds_read_b64_tr_b16 v[220:221], v254 offset:0
	ds_read_b64_tr_b16 v[222:223], v254 offset:2048
	ds_read_b64_tr_b16 v[224:225], v254 offset:4096
	ds_read_b64_tr_b16 v[226:227], v254 offset:6144
	ds_read_b64_tr_b16 v[228:229], v254 offset:8192
	ds_read_b64_tr_b16 v[230:231], v254 offset:10240
	ds_read_b64_tr_b16 v[232:233], v254 offset:12288
	ds_read_b64_tr_b16 v[234:235], v254 offset:14336
	ds_read_b64_tr_b16 v[236:237], v254 offset:512
	ds_read_b64_tr_b16 v[238:239], v254 offset:2560
	s_waitcnt lgkmcnt(6)
	v_mfma_f32_32x32x16_bf16 v[52:67], v[216:219], v[220:223], v[52:67]
	ds_read_b64_tr_b16 v[240:241], v254 offset:4608
	ds_read_b64_tr_b16 v[242:243], v254 offset:6656
	v_mfma_f32_32x32x16_bf16 v[52:67], v[208:211], v[224:227], v[52:67]
	ds_read_b64_tr_b16 v[220:221], v254 offset:8704
	ds_read_b64_tr_b16 v[222:223], v254 offset:10752
	s_waitcnt lgkmcnt(6)
	v_mfma_f32_32x32x16_bf16 v[52:67], v[202:205], v[228:231], v[52:67]
	ds_read_b64_tr_b16 v[224:225], v254 offset:12800
	ds_read_b64_tr_b16 v[226:227], v254 offset:14848
	v_mfma_f32_32x32x16_bf16 v[52:67], v[212:215], v[232:235], v[52:67]
	ds_read_b64_tr_b16 v[228:229], v254 offset:1024
	ds_read_b64_tr_b16 v[230:231], v254 offset:3072
	s_waitcnt lgkmcnt(6)
	v_mfma_f32_32x32x16_bf16 v[36:51], v[216:219], v[236:239], v[36:51]
	ds_read_b64_tr_b16 v[232:233], v254 offset:5120
	ds_read_b64_tr_b16 v[234:235], v254 offset:7168
	v_mfma_f32_32x32x16_bf16 v[36:51], v[208:211], v[240:243], v[36:51]
	ds_read_b64_tr_b16 v[236:237], v254 offset:9216
	ds_read_b64_tr_b16 v[238:239], v254 offset:11264
	s_waitcnt lgkmcnt(6)
	v_mfma_f32_32x32x16_bf16 v[36:51], v[202:205], v[220:223], v[36:51]
	ds_read_b64_tr_b16 v[240:241], v254 offset:13312
	ds_read_b64_tr_b16 v[242:243], v254 offset:15360
	v_mfma_f32_32x32x16_bf16 v[36:51], v[212:215], v[224:227], v[36:51]
	ds_read_b64_tr_b16 v[220:221], v254 offset:1536
	ds_read_b64_tr_b16 v[222:223], v254 offset:3584
	s_waitcnt lgkmcnt(6)
	v_mfma_f32_32x32x16_bf16 v[20:35], v[216:219], v[228:231], v[20:35]
	ds_read_b64_tr_b16 v[224:225], v254 offset:5632
	ds_read_b64_tr_b16 v[226:227], v254 offset:7680
	v_mfma_f32_32x32x16_bf16 v[20:35], v[208:211], v[232:235], v[20:35]
	ds_read_b64_tr_b16 v[228:229], v254 offset:9728
	ds_read_b64_tr_b16 v[230:231], v254 offset:11776
	s_waitcnt lgkmcnt(6)
	v_mfma_f32_32x32x16_bf16 v[20:35], v[202:205], v[236:239], v[20:35]
	ds_read_b64_tr_b16 v[232:233], v254 offset:13824
	ds_read_b64_tr_b16 v[234:235], v254 offset:15872
	v_mfma_f32_32x32x16_bf16 v[20:35], v[212:215], v[240:243], v[20:35]
	s_waitcnt lgkmcnt(4)
	v_mfma_f32_32x32x16_bf16 v[4:19], v[216:219], v[220:223], v[4:19]
	s_waitcnt vmcnt(4)
	v_mfma_f32_32x32x16_bf16 v[4:19], v[208:211], v[224:227], v[4:19]
	s_waitcnt lgkmcnt(0)
	v_mfma_f32_32x32x16_bf16 v[4:19], v[202:205], v[228:231], v[4:19]
	v_mfma_f32_32x32x16_bf16 v[4:19], v[212:215], v[232:235], v[4:19]
	s_setprio 0
	s_lshl_b32 s92, s66, 14
	s_add_i32 s95, s92, 0
	v_add_u32_e32 v203, s95, v184
	ds_write_b128 v203, v[136:139]
	v_add_u32_e32 v136, s95, v186
	ds_write_b128 v136, v[132:135]
	v_add_u32_e32 v132, s95, v187
	ds_write_b128 v132, v[144:147] offset:49152
	v_add_u32_e32 v132, s95, v188
	s_waitcnt vmcnt(4)
	ds_write_b128 v132, v[140:143] offset:49152
	s_waitcnt lgkmcnt(0)
	s_barrier
	v_max_f32_e32 v2, v85, v85
	v_max_f32_e32 v202, v84, v84
	v_max_f32_e32 v2, v202, v2
	v_max3_f32 v2, v2, v86, v87
	v_max3_f32 v2, v2, v88, v89
	v_max3_f32 v2, v2, v90, v91
	v_max3_f32 v2, v2, v92, v93
	v_max3_f32 v2, v2, v94, v95
	v_max3_f32 v2, v2, v96, v97
	v_max3_f32 v2, v2, v98, v99
	v_max3_f32 v2, v2, v68, v69
	v_max3_f32 v2, v2, v70, v71
	v_max3_f32 v2, v2, v72, v73
	v_max3_f32 v2, v2, v74, v75
	v_max3_f32 v2, v2, v76, v77
	v_max3_f32 v2, v2, v78, v79
	v_max3_f32 v2, v2, v80, v81
	v_max3_f32 v2, v2, v82, v83
	v_mov_b32_e32 v202, v2
	s_nop 1
	v_permlane32_swap_b32_e32 v2, v202
	v_max_f32_e32 v202, v202, v202
	v_max_f32_e32 v2, v2, v2
	v_max_f32_e32 v2, v2, v202
	v_sub_f32_e32 v202, v2, v166
	v_cmp_ge_f32_e32 vcc, s74, v202
	v_max_f32_e32 v202, v166, v166
	v_max_f32_e32 v2, v202, v2
	v_sub_f32_e32 v202, v166, v2
	s_cmp_eq_u64 vcc, exec
	v_mul_f32_e32 v202, 0x3e0293ee, v202
	s_cselect_b64 s[6:7], -1, 0
	v_exp_f32_e32 v202, v202
	s_nop 0
	v_cndmask_b32_e64 v202, v202, 1.0, s[6:7]
	v_cmp_gt_f32_e32 vcc, 1.0, v202
	s_cbranch_vccz .Lstg_r1
	s_and_saveexec_b64 s[66:67], s[4:5]
	ds_write_b32 v183, v202 offset:128
	s_or_b64 exec, exec, s[66:67]
	s_waitcnt lgkmcnt(0)
	v_add_u32_e32 v144, v181, v180
	ds_read_b128 v[132:135], v144 offset:224
	ds_read_b128 v[136:139], v144 offset:192
	ds_read_b128 v[140:143], v144 offset:160
	ds_read_b128 v[144:147], v144 offset:128
	s_waitcnt lgkmcnt(3)
	v_pk_mul_f32 v[64:65], v[64:65], v[132:133]
	s_waitcnt lgkmcnt(2)
	v_pk_mul_f32 v[60:61], v[60:61], v[136:137]
	s_waitcnt lgkmcnt(1)
	v_pk_mul_f32 v[56:57], v[56:57], v[140:141]
	v_pk_mul_f32 v[66:67], v[66:67], v[134:135]
	v_pk_mul_f32 v[62:63], v[62:63], v[138:139]
	v_pk_mul_f32 v[58:59], v[58:59], v[142:143]
	s_waitcnt lgkmcnt(0)
	v_pk_mul_f32 v[54:55], v[54:55], v[146:147]
	v_pk_mul_f32 v[52:53], v[52:53], v[144:145]
	v_pk_mul_f32 v[48:49], v[48:49], v[132:133]
	v_pk_mul_f32 v[44:45], v[44:45], v[136:137]
	v_pk_mul_f32 v[40:41], v[40:41], v[140:141]
	v_pk_mul_f32 v[50:51], v[50:51], v[134:135]
	v_pk_mul_f32 v[46:47], v[46:47], v[138:139]
	v_pk_mul_f32 v[42:43], v[42:43], v[142:143]
	v_pk_mul_f32 v[38:39], v[38:39], v[146:147]
	v_pk_mul_f32 v[36:37], v[36:37], v[144:145]
	v_pk_mul_f32 v[32:33], v[32:33], v[132:133]
	v_pk_mul_f32 v[28:29], v[28:29], v[136:137]
	v_pk_mul_f32 v[24:25], v[24:25], v[140:141]
	v_pk_mul_f32 v[34:35], v[34:35], v[134:135]
	v_pk_mul_f32 v[30:31], v[30:31], v[138:139]
	v_pk_mul_f32 v[26:27], v[26:27], v[142:143]
	v_pk_mul_f32 v[22:23], v[22:23], v[146:147]
	v_pk_mul_f32 v[20:21], v[20:21], v[144:145]
	v_pk_mul_f32 v[16:17], v[16:17], v[132:133]
	v_pk_mul_f32 v[12:13], v[12:13], v[136:137]
	v_pk_mul_f32 v[8:9], v[8:9], v[140:141]
	v_pk_mul_f32 v[18:19], v[18:19], v[134:135]
	v_pk_mul_f32 v[14:15], v[14:15], v[138:139]
	v_pk_mul_f32 v[10:11], v[10:11], v[142:143]
	v_pk_mul_f32 v[6:7], v[6:7], v[146:147]
	v_pk_mul_f32 v[4:5], v[4:5], v[144:145]
; __device__ __forceinline__ void partialSM(f32x16& p0, f32x16& p1, float& m_reg, float& mn, float& alpha) {
;   constexpr float C = SCALE * 1.4426950408889634f;
;   float pmax = p0[0]; for (int r = 1; r < 16; ++r) pmax = fmaxf(pmax, p0[r]); for (int r = 0; r < 16; ++r) pmax = fmaxf(pmax, p1[r]);
;   { auto rr = __builtin_amdgcn_permlane32_swap(__float_as_uint(pmax), __float_as_uint(pmax), false, false);
;     pmax = fmaxf(__uint_as_float(rr[0]), __uint_as_float(rr[1])); }
;   if (__builtin_expect(__all(pmax - m_reg <= THR / SCALE), 1)) { mn = m_reg; alpha = 1.f; }
;   else { mn = fmaxf(m_reg, pmax); alpha = __builtin_amdgcn_exp2f((m_reg - mn) * C); m_reg = mn; }
;   float mnC = -mn * C;
;   for (int r = 0; r < 16; ++r) p0[r] = fmaf(p0[r], C, mnC); for (int r = 0; r < 16; ++r) p1[r] = fmaf(p1[r], C, mnC);
;   for (int r = 0; r < 16; ++r) p0[r] = __builtin_amdgcn_exp2f(p0[r]);
; }
; __device__ __forceinline__ void finishSM(f32x16& p0, f32x16& p1, float alpha, float& l_reg, bf16x8& pa0, bf16x8& pa1, bf16x8& pa2, bf16x8& pa3) {
;   for (int r = 0; r < 16; ++r) p1[r] = __builtin_amdgcn_exp2f(p1[r]);
;   float ps = 0; for (int r = 0; r < 16; ++r) ps += p0[r]; for (int r = 0; r < 16; ++r) ps += p1[r];
;   { auto rr = __builtin_amdgcn_permlane32_swap(__float_as_uint(ps), __float_as_uint(ps), false, false);
;     ps = __uint_as_float(rr[0]) + __uint_as_float(rr[1]); }
;   l_reg = l_reg * alpha + ps;
;     ...
;   PK4(p0, 0, pa0); PK4(p0, 8, pa1); PK4(p1, 0, pa2); PK4(p1, 8, pa3);
;     ...
; }
; __device__ __forceinline__ void qkt(f32x16& p0, f32x16& p1, const u16* Ks, const bf16x8* qr, int r32, int hi) {
;   p0 = f32x16{}; p1 = f32x16{};
;   for (int d0 = 0; d0 < 8; ++d0) { int cb = (d0 * 16 + hi * 8) * 2;
;     bf16x8 b0 = *reinterpret_cast<const bf16x8*>((const char*)Ks + KSWZ(r32, cb));
;     bf16x8 b1 = *reinterpret_cast<const bf16x8*>((const char*)Ks + KSWZ(32 + r32, cb));
;     p0 = __builtin_amdgcn_mfma_f32_32x32x16_bf16(b0, qr[d0], p0, 0, 0, 0);
;     p1 = __builtin_amdgcn_mfma_f32_32x32x16_bf16(b1, qr[d0], p1, 0, 0, 0); }
; }
.Lstg_r1:
	v_cndmask_b32_e64 v2, v2, v166, s[6:7]
	v_mul_f32_e32 v140, 0xbe0293ee, v2
	v_fmamk_f32 v93, v93, 0x3e0293ee, v140
	v_exp_f32_e32 v221, v93
	v_fmamk_f32 v84, v84, 0x3e0293ee, v140
	v_fmamk_f32 v85, v85, 0x3e0293ee, v140
	v_fmamk_f32 v86, v86, 0x3e0293ee, v140
	v_fmamk_f32 v87, v87, 0x3e0293ee, v140
	v_fmamk_f32 v88, v88, 0x3e0293ee, v140
	v_fmamk_f32 v89, v89, 0x3e0293ee, v140
	v_fmamk_f32 v90, v90, 0x3e0293ee, v140
	v_fmamk_f32 v91, v91, 0x3e0293ee, v140
	v_fmamk_f32 v92, v92, 0x3e0293ee, v140
	v_fmamk_f32 v94, v94, 0x3e0293ee, v140
	v_fmamk_f32 v95, v95, 0x3e0293ee, v140
	v_fmamk_f32 v96, v96, 0x3e0293ee, v140
	v_fmamk_f32 v97, v97, 0x3e0293ee, v140
	v_fmamk_f32 v98, v98, 0x3e0293ee, v140
	v_fmamk_f32 v99, v99, 0x3e0293ee, v140
	v_fmamk_f32 v141, v68, 0x3e0293ee, v140
	v_fmamk_f32 v142, v69, 0x3e0293ee, v140
	v_fmamk_f32 v143, v70, 0x3e0293ee, v140
	v_fmamk_f32 v144, v71, 0x3e0293ee, v140
	v_fmamk_f32 v145, v72, 0x3e0293ee, v140
	v_fmamk_f32 v146, v73, 0x3e0293ee, v140
	v_fmamk_f32 v147, v74, 0x3e0293ee, v140
	v_fmamk_f32 v166, v75, 0x3e0293ee, v140
	v_fmamk_f32 v203, v76, 0x3e0293ee, v140
	v_fmamk_f32 v204, v77, 0x3e0293ee, v140
	v_fmamk_f32 v205, v78, 0x3e0293ee, v140
	v_fmamk_f32 v206, v79, 0x3e0293ee, v140
	v_fmamk_f32 v207, v80, 0x3e0293ee, v140
	v_fmamk_f32 v208, v81, 0x3e0293ee, v140
	v_fmamk_f32 v209, v82, 0x3e0293ee, v140
	v_fmac_f32_e32 v140, 0x3e0293ee, v83
	v_exp_f32_e32 v210, v84
	v_exp_f32_e32 v211, v85
	v_exp_f32_e32 v212, v86
	v_exp_f32_e32 v213, v87
	v_exp_f32_e32 v214, v88
	v_exp_f32_e32 v215, v89
	v_exp_f32_e32 v216, v90
	v_exp_f32_e32 v217, v91
	v_exp_f32_e32 v218, v92
	v_exp_f32_e32 v222, v94
	v_exp_f32_e32 v223, v95
	v_exp_f32_e32 v224, v96
	v_exp_f32_e32 v225, v97
	v_exp_f32_e32 v226, v98
	v_exp_f32_e32 v227, v99
	s_barrier
	s_setprio 1
	v_add_u32_e32 v254, s95, v189
	ds_read_b128 v[68:71], v254 offset:49152
	ds_read_b128 v[72:75], v254 offset:49280
	v_add_u32_e32 v254, s95, v190
	ds_read_b128 v[76:79], v254 offset:49152
	ds_read_b128 v[80:83], v254 offset:49280
	v_add_u32_e32 v254, s95, v191
	ds_read_b128 v[228:231], v254 offset:49152
	ds_read_b128 v[232:235], v254 offset:49280
	v_add_u32_e32 v254, s95, v192
	ds_read_b128 v[236:239], v254 offset:49152
	ds_read_b128 v[240:243], v254 offset:49280
	v_add_u32_e32 v254, s95, v189
	ds_read_b128 v[246:249], v254 offset:57344
	ds_read_b128 v[250:253], v254 offset:57472
	s_waitcnt lgkmcnt(9)
	v_mfma_f32_32x32x16_bf16 v[84:99], v[68:71], v[100:103], 0
	s_waitcnt lgkmcnt(8)
	v_mfma_f32_32x32x16_bf16 v[84:99], v[72:75], v[116:119], v[84:99]
	s_waitcnt lgkmcnt(7)
	v_mfma_f32_32x32x16_bf16 v[84:99], v[76:79], v[104:107], v[84:99]
	s_waitcnt lgkmcnt(6)
	v_mfma_f32_32x32x16_bf16 v[84:99], v[80:83], v[120:123], v[84:99]
	s_waitcnt lgkmcnt(5)
	v_mfma_f32_32x32x16_bf16 v[84:99], v[228:231], v[108:111], v[84:99]
	v_add_u32_e32 v254, s95, v190
	ds_read_b128 v[228:231], v254 offset:57344
	s_waitcnt lgkmcnt(5)
	v_mfma_f32_32x32x16_bf16 v[84:99], v[232:235], v[124:127], v[84:99]
	ds_read_b128 v[232:235], v254 offset:57472
	s_waitcnt lgkmcnt(5)
	v_mfma_f32_32x32x16_bf16 v[84:99], v[236:239], v[112:115], v[84:99]
	v_add_u32_e32 v254, s95, v191
	ds_read_b128 v[236:239], v254 offset:57344
	s_waitcnt lgkmcnt(5)
	v_mfma_f32_32x32x16_bf16 v[84:99], v[240:243], v[128:131], v[84:99]
	ds_read_b128 v[240:243], v254 offset:57472
	s_waitcnt lgkmcnt(5)
	v_mfma_f32_32x32x16_bf16 v[68:83], v[246:249], v[100:103], 0
	v_add_u32_e32 v254, s95, v192
	ds_read_b128 v[246:249], v254 offset:57344
	s_waitcnt lgkmcnt(5)
	v_mfma_f32_32x32x16_bf16 v[68:83], v[250:253], v[116:119], v[68:83]
	ds_read_b128 v[250:253], v254 offset:57472
	s_waitcnt lgkmcnt(5)
	v_mfma_f32_32x32x16_bf16 v[68:83], v[228:231], v[104:107], v[68:83]
	s_waitcnt lgkmcnt(4)
	v_mfma_f32_32x32x16_bf16 v[68:83], v[232:235], v[120:123], v[68:83]
	s_waitcnt lgkmcnt(3)
	v_mfma_f32_32x32x16_bf16 v[68:83], v[236:239], v[108:111], v[68:83]
	s_waitcnt lgkmcnt(2)
	v_mfma_f32_32x32x16_bf16 v[68:83], v[240:243], v[124:127], v[68:83]
	s_waitcnt lgkmcnt(1)
	v_mfma_f32_32x32x16_bf16 v[68:83], v[246:249], v[112:115], v[68:83]
	s_waitcnt lgkmcnt(0)
	v_mfma_f32_32x32x16_bf16 v[68:83], v[250:253], v[128:131], v[68:83]
	s_setprio 0
	s_barrier
	v_exp_f32_e32 v140, v140
	v_exp_f32_e32 v139, v166
	v_add_f32_e32 v166, 0, v210
	v_add_f32_e32 v166, v211, v166
	v_add_f32_e32 v166, v212, v166
	v_add_f32_e32 v166, v213, v166
	v_add_f32_e32 v166, v214, v166
	v_add_f32_e32 v166, v215, v166
	v_add_f32_e32 v166, v216, v166
	v_add_f32_e32 v166, v217, v166
	v_add_f32_e32 v166, v218, v166
	v_add_f32_e32 v166, v221, v166
	v_add_f32_e32 v166, v222, v166
	v_add_f32_e32 v166, v223, v166
	v_exp_f32_e32 v132, v141
	v_add_f32_e32 v166, v224, v166
	v_exp_f32_e32 v133, v142
	v_add_f32_e32 v166, v225, v166
	v_exp_f32_e32 v134, v143
	v_add_f32_e32 v166, v226, v166
	v_exp_f32_e32 v135, v144
	v_add_f32_e32 v166, v227, v166
	v_exp_f32_e32 v136, v145
	v_add_f32_e32 v166, v132, v166
	v_exp_f32_e32 v137, v146
	v_add_f32_e32 v166, v133, v166
	v_exp_f32_e32 v138, v147
	v_add_f32_e32 v166, v134, v166
	v_add_f32_e32 v166, v135, v166
	v_exp_f32_e32 v141, v203
	v_add_f32_e32 v166, v136, v166
	v_exp_f32_e32 v142, v204
	v_add_f32_e32 v166, v137, v166
	v_exp_f32_e32 v143, v205
	v_add_f32_e32 v166, v138, v166
	v_exp_f32_e32 v144, v206
	v_add_f32_e32 v166, v139, v166
	v_exp_f32_e32 v145, v207
	v_add_f32_e32 v166, v141, v166
	v_exp_f32_e32 v146, v208
	v_add_f32_e32 v166, v142, v166
	v_exp_f32_e32 v147, v209
	v_add_f32_e32 v166, v143, v166
	v_add_f32_e32 v166, v144, v166
	v_add_f32_e32 v166, v145, v166
	v_add_f32_e32 v166, v146, v166
	v_add_f32_e32 v166, v147, v166
	v_add_f32_e32 v219, v140, v166
	v_mov_b32_e32 v220, v219
	s_nop 1
	v_permlane32_swap_b32_e32 v219, v220
	v_cvt_pk_bf16_f32 v204, v210, v211
	v_cvt_pk_bf16_f32 v205, v212, v213
	v_cvt_pk_bf16_f32 v206, v214, v215
	v_cvt_pk_bf16_f32 v207, v216, v217
	v_cvt_pk_bf16_f32 v208, v218, v221
	v_cvt_pk_bf16_f32 v209, v222, v223
	v_cvt_pk_bf16_f32 v210, v224, v225
	v_cvt_pk_bf16_f32 v211, v226, v227
	v_cvt_pk_bf16_f32 v212, v132, v133
	v_cvt_pk_bf16_f32 v213, v134, v135
	v_cvt_pk_bf16_f32 v214, v136, v137
	v_cvt_pk_bf16_f32 v215, v138, v139
	v_cvt_pk_bf16_f32 v222, v141, v142
	v_cvt_pk_bf16_f32 v223, v143, v144
	v_cvt_pk_bf16_f32 v224, v145, v146
	v_cvt_pk_bf16_f32 v225, v147, v140
	s_nop 0
	v_permlane32_swap_b32_e32 v204, v206
	v_permlane32_swap_b32_e32 v205, v207
	v_permlane32_swap_b32_e32 v208, v210
	v_permlane32_swap_b32_e32 v209, v211
	v_permlane32_swap_b32_e32 v212, v214
	v_permlane32_swap_b32_e32 v213, v215
	v_permlane32_swap_b32_e32 v222, v224
	v_permlane32_swap_b32_e32 v223, v225
	s_min_u32 s7, s16, s90
	s_add_i32 s7, s7, s88
	s_lshl_b32 s7, s7, 6
	v_add_u32_e32 v244, s7, v167
	v_add_u32_e32 v245, s7, v185
	v_lshl_or_b32 v244, v244, 8, v182
	v_lshl_or_b32 v245, v245, 8, v182
	global_load_dwordx4 v[136:139], v244, s[58:59]
	global_load_dwordx4 v[132:135], v245, s[58:59]
	global_load_dwordx4 v[144:147], v244, s[64:65]
	global_load_dwordx4 v[140:143], v245, s[64:65]
	s_barrier
; #define SBAR() __builtin_amdgcn_sched_barrier(0)
; __device__ __forceinline__ void partialSM(f32x16& p0, f32x16& p1, float& m_reg, float& mn, float& alpha) {
;   constexpr float C = SCALE * 1.4426950408889634f;
;   float pmax = p0[0]; for (int r = 1; r < 16; ++r) pmax = fmaxf(pmax, p0[r]); for (int r = 0; r < 16; ++r) pmax = fmaxf(pmax, p1[r]);
;   { auto rr = __builtin_amdgcn_permlane32_swap(__float_as_uint(pmax), __float_as_uint(pmax), false, false);
;     pmax = fmaxf(__uint_as_float(rr[0]), __uint_as_float(rr[1])); }
;   if (__builtin_expect(__all(pmax - m_reg <= THR / SCALE), 1)) { mn = m_reg; alpha = 1.f; }
;   else { mn = fmaxf(m_reg, pmax); alpha = __builtin_amdgcn_exp2f((m_reg - mn) * C); m_reg = mn; }
; template <int OFF> __device__ __forceinline__ s16x4 tr_read(int vb) {
;   s16x4 r; asm volatile("ds_read_b64_tr_b16 %0, %1 offset:%2" : "=&v"(r) : "v"(vb), "i"(OFF) : "memory"); return r;
; }
; template <int D0> __device__ __forceinline__ void pv_one(f32x16& od, int vb, bf16x8 pa0, bf16x8 pa1, bf16x8 pa2, bf16x8 pa3) {
;   const s16x4 l0 = tr_read<v_rd_off(D0, 0, 0)>(vb), h0 = tr_read<v_rd_off(D0, 0, 1)>(vb), l1 = tr_read<v_rd_off(D0, 1, 0)>(vb), h1 = tr_read<v_rd_off(D0, 1, 1)>(vb);
;   const s16x4 l2 = tr_read<v_rd_off(D0, 2, 0)>(vb), h2 = tr_read<v_rd_off(D0, 2, 1)>(vb), l3 = tr_read<v_rd_off(D0, 3, 0)>(vb), h3 = tr_read<v_rd_off(D0, 3, 1)>(vb);
;   asm volatile("s_waitcnt lgkmcnt(0)" ::: "memory"); SBAR();
;     ...
;   od = __builtin_amdgcn_mfma_f32_32x32x16_bf16(pa0, PK(l0, h0), od, 0, 0, 0);
;   od = __builtin_amdgcn_mfma_f32_32x32x16_bf16(pa1, PK(l1, h1), od, 0, 0, 0);
;   od = __builtin_amdgcn_mfma_f32_32x32x16_bf16(pa2, PK(l2, h2), od, 0, 0, 0);
;   od = __builtin_amdgcn_mfma_f32_32x32x16_bf16(pa3, PK(l3, h3), od, 0, 0, 0);
;     ...
; }
; __device__ __forceinline__ void pv_d0(f32x16* o, int vb, bf16x8 pa0, bf16x8 pa1, bf16x8 pa2, bf16x8 pa3) {
;   pv_one<0>(o[0], vb, pa0, pa1, pa2, pa3); pv_one<1>(o[1], vb, pa0, pa1, pa2, pa3); pv_one<2>(o[2], vb, pa0, pa1, pa2, pa3); pv_one<3>(o[3], vb, pa0, pa1, pa2, pa3);
	s_setprio 1
	v_add_u32_e32 v254, s93, v197
	ds_read_b64_tr_b16 v[230:231], v254 offset:0
	ds_read_b64_tr_b16 v[232:233], v254 offset:2048
	ds_read_b64_tr_b16 v[234:235], v254 offset:4096
	ds_read_b64_tr_b16 v[236:237], v254 offset:6144
	ds_read_b64_tr_b16 v[238:239], v254 offset:8192
	ds_read_b64_tr_b16 v[240:241], v254 offset:10240
	ds_read_b64_tr_b16 v[242:243], v254 offset:12288
	ds_read_b64_tr_b16 v[244:245], v254 offset:14336
	ds_read_b64_tr_b16 v[246:247], v254 offset:512
	ds_read_b64_tr_b16 v[248:249], v254 offset:2560
	s_waitcnt lgkmcnt(6)
	v_mfma_f32_32x32x16_bf16 v[52:67], v[204:207], v[230:233], v[52:67]
	ds_read_b64_tr_b16 v[250:251], v254 offset:4608
	ds_read_b64_tr_b16 v[252:253], v254 offset:6656
	v_mfma_f32_32x32x16_bf16 v[52:67], v[208:211], v[234:237], v[52:67]
	ds_read_b64_tr_b16 v[230:231], v254 offset:8704
	ds_read_b64_tr_b16 v[232:233], v254 offset:10752
	s_waitcnt lgkmcnt(6)
	v_mfma_f32_32x32x16_bf16 v[52:67], v[212:215], v[238:241], v[52:67]
	ds_read_b64_tr_b16 v[234:235], v254 offset:12800
	ds_read_b64_tr_b16 v[236:237], v254 offset:14848
	v_mfma_f32_32x32x16_bf16 v[52:67], v[222:225], v[242:245], v[52:67]
	ds_read_b64_tr_b16 v[238:239], v254 offset:1024
	ds_read_b64_tr_b16 v[240:241], v254 offset:3072
	s_waitcnt lgkmcnt(6)
	v_mfma_f32_32x32x16_bf16 v[36:51], v[204:207], v[246:249], v[36:51]
	ds_read_b64_tr_b16 v[242:243], v254 offset:5120
	ds_read_b64_tr_b16 v[244:245], v254 offset:7168
	v_mfma_f32_32x32x16_bf16 v[36:51], v[208:211], v[250:253], v[36:51]
	ds_read_b64_tr_b16 v[246:247], v254 offset:9216
	ds_read_b64_tr_b16 v[248:249], v254 offset:11264
	s_waitcnt lgkmcnt(6)
	v_mfma_f32_32x32x16_bf16 v[36:51], v[212:215], v[230:233], v[36:51]
	ds_read_b64_tr_b16 v[250:251], v254 offset:13312
	ds_read_b64_tr_b16 v[252:253], v254 offset:15360
	v_mfma_f32_32x32x16_bf16 v[36:51], v[222:225], v[234:237], v[36:51]
	ds_read_b64_tr_b16 v[230:231], v254 offset:1536
	ds_read_b64_tr_b16 v[232:233], v254 offset:3584
	s_waitcnt lgkmcnt(6)
	v_mfma_f32_32x32x16_bf16 v[20:35], v[204:207], v[238:241], v[20:35]
	ds_read_b64_tr_b16 v[234:235], v254 offset:5632
	ds_read_b64_tr_b16 v[236:237], v254 offset:7680
	v_mfma_f32_32x32x16_bf16 v[20:35], v[208:211], v[242:245], v[20:35]
	ds_read_b64_tr_b16 v[238:239], v254 offset:9728
	ds_read_b64_tr_b16 v[240:241], v254 offset:11776
	s_waitcnt lgkmcnt(6)
	v_mfma_f32_32x32x16_bf16 v[20:35], v[212:215], v[246:249], v[20:35]
	ds_read_b64_tr_b16 v[242:243], v254 offset:13824
	ds_read_b64_tr_b16 v[244:245], v254 offset:15872
	v_mfma_f32_32x32x16_bf16 v[20:35], v[222:225], v[250:253], v[20:35]
	s_waitcnt lgkmcnt(4)
	v_mfma_f32_32x32x16_bf16 v[4:19], v[204:207], v[230:233], v[4:19]
	v_mfma_f32_32x32x16_bf16 v[4:19], v[208:211], v[234:237], v[4:19]
	s_waitcnt lgkmcnt(0)
	v_mfma_f32_32x32x16_bf16 v[4:19], v[212:215], v[238:241], v[4:19]
	v_mfma_f32_32x32x16_bf16 v[4:19], v[222:225], v[242:245], v[4:19]
	s_setprio 0
	s_add_i32 s30, s94, 0
	v_add_u32_e32 v203, s30, v184
	s_waitcnt vmcnt(4)
	ds_write_b128 v203, v[152:155]
	v_add_u32_e32 v152, s30, v186
	ds_write_b128 v152, v[148:151]
	v_add_u32_e32 v148, s30, v187
	ds_write_b128 v148, v[160:163] offset:49152
	v_add_u32_e32 v148, s30, v188
	s_waitcnt vmcnt(4)
	ds_write_b128 v148, v[156:159] offset:49152
	s_waitcnt lgkmcnt(0)
	s_barrier
	v_max_f32_e32 v166, v85, v85
	v_max_f32_e32 v203, v84, v84
	v_max_f32_e32 v166, v203, v166
	v_max3_f32 v166, v166, v86, v87
	v_max3_f32 v166, v166, v88, v89
	v_max3_f32 v166, v166, v90, v91
	v_max3_f32 v166, v166, v92, v93
	v_max3_f32 v166, v166, v94, v95
	v_max3_f32 v166, v166, v96, v97
	v_max3_f32 v166, v166, v98, v99
	v_max3_f32 v166, v166, v68, v69
	v_max3_f32 v166, v166, v70, v71
	v_max3_f32 v166, v166, v72, v73
	v_max3_f32 v166, v166, v74, v75
	v_max3_f32 v166, v166, v76, v77
	v_max3_f32 v166, v166, v78, v79
	v_max3_f32 v166, v166, v80, v81
	v_max3_f32 v166, v166, v82, v83
	v_mov_b32_e32 v203, v166
	s_nop 1
	v_permlane32_swap_b32_e32 v166, v203
	v_max_f32_e32 v203, v203, v203
	v_max_f32_e32 v166, v166, v166
	v_max_f32_e32 v166, v166, v203
	v_sub_f32_e32 v203, v166, v2
	v_cmp_ge_f32_e32 vcc, s74, v203
	v_max_f32_e32 v203, v2, v2
	v_max_f32_e32 v166, v203, v166
	v_sub_f32_e32 v203, v2, v166
	v_mul_f32_e32 v203, 0x3e0293ee, v203
	v_exp_f32_e32 v203, v203
	s_cmp_eq_u64 vcc, exec
	s_cselect_b64 s[6:7], -1, 0
	v_cndmask_b32_e64 v221, v203, 1.0, s[6:7]
	v_cmp_gt_f32_e32 vcc, 1.0, v221
	s_cbranch_vccz .Lstg_r2
	s_and_saveexec_b64 s[66:67], s[4:5]
	ds_write_b32 v183, v221 offset:128
	s_or_b64 exec, exec, s[66:67]
	s_waitcnt lgkmcnt(0)
	v_add_u32_e32 v160, v181, v180
	ds_read_b128 v[148:151], v160 offset:224
	ds_read_b128 v[152:155], v160 offset:192
	ds_read_b128 v[156:159], v160 offset:160
	ds_read_b128 v[160:163], v160 offset:128
	s_waitcnt lgkmcnt(3)
	v_pk_mul_f32 v[64:65], v[64:65], v[148:149]
	s_waitcnt lgkmcnt(2)
	v_pk_mul_f32 v[60:61], v[60:61], v[152:153]
	s_waitcnt lgkmcnt(1)
	v_pk_mul_f32 v[56:57], v[56:57], v[156:157]
	v_pk_mul_f32 v[66:67], v[66:67], v[150:151]
	v_pk_mul_f32 v[62:63], v[62:63], v[154:155]
	v_pk_mul_f32 v[58:59], v[58:59], v[158:159]
	s_waitcnt lgkmcnt(0)
	v_pk_mul_f32 v[54:55], v[54:55], v[162:163]
	v_pk_mul_f32 v[52:53], v[52:53], v[160:161]
	v_pk_mul_f32 v[48:49], v[48:49], v[148:149]
	v_pk_mul_f32 v[44:45], v[44:45], v[152:153]
	v_pk_mul_f32 v[40:41], v[40:41], v[156:157]
	v_pk_mul_f32 v[50:51], v[50:51], v[150:151]
	v_pk_mul_f32 v[46:47], v[46:47], v[154:155]
	v_pk_mul_f32 v[42:43], v[42:43], v[158:159]
	v_pk_mul_f32 v[38:39], v[38:39], v[162:163]
	v_pk_mul_f32 v[36:37], v[36:37], v[160:161]
	v_pk_mul_f32 v[32:33], v[32:33], v[148:149]
	v_pk_mul_f32 v[28:29], v[28:29], v[152:153]
	v_pk_mul_f32 v[24:25], v[24:25], v[156:157]
	v_pk_mul_f32 v[34:35], v[34:35], v[150:151]
	v_pk_mul_f32 v[30:31], v[30:31], v[154:155]
	v_pk_mul_f32 v[26:27], v[26:27], v[158:159]
	v_pk_mul_f32 v[22:23], v[22:23], v[162:163]
	v_pk_mul_f32 v[20:21], v[20:21], v[160:161]
	v_pk_mul_f32 v[16:17], v[16:17], v[148:149]
	v_pk_mul_f32 v[12:13], v[12:13], v[152:153]
	v_pk_mul_f32 v[8:9], v[8:9], v[156:157]
	v_pk_mul_f32 v[18:19], v[18:19], v[150:151]
	v_pk_mul_f32 v[14:15], v[14:15], v[154:155]
	v_pk_mul_f32 v[10:11], v[10:11], v[158:159]
	v_pk_mul_f32 v[6:7], v[6:7], v[162:163]
	v_pk_mul_f32 v[4:5], v[4:5], v[160:161]
